# v19 plus batched ds_bpermute rounds and batched subw loads in the attention map-1 epilogue (de-serialised epilogue chains)
# baseline (speedup 1.0000x reference)
; #define A128_SBAR() __builtin_amdgcn_sched_barrier(0)
; __device__ __forceinline__ int crow(int r, int hi) { return (r & 3) + 8 * (r >> 2) + 4 * hi; }
; #define A128_RESC(a) do { if (__any((a) < 1.f)) { if (hi == 0) al_l[r32] = (a); asm volatile("s_waitcnt lgkmcnt(0)" ::: "memory"); \
;     _Pragma("unroll") for (int d = 0; d < 4; ++d) _Pragma("unroll") for (int r = 0; r < 16; ++r) o[d][r] *= al_l[crow(r, hi)]; } } while (0)
; __device__ __forceinline__ void unit(const bf16* __restrict__ Qb0, const bf16* __restrict__ Kh0, const bf16* __restrict__ Vh, bf16_t* Ob, int seq, char* lds, const int tid_in, const float lam, const float onem, const float* __restrict__ subw, const float* __restrict__ kmb  ) {
;     ...
;   finishSM(pA0, pA1, alA, l_reg, pa0, pa1, pa2, pa3); A128_SBAR();
;   pv_d0(o, vb0, pa0, pa1, pa2, pa3); partialSM(pB0, pB1, m_reg, mnB, alB, nomax);
;   __syncthreads(); if (!nomax) A128_RESC(alB);
;   finishSM(pB0, pB1, alB, l_reg, pa0, pa1, pa2, pa3); A128_SBAR();
;   pv_d0(o, vb0 + (int)SHM_V, pa0, pa1, pa2, pa3);
;   if (hi == 0) li_l[r32] = l_reg; asm volatile("s_waitcnt lgkmcnt(0)" ::: "memory");
;   float rli[16];
; #pragma unroll
;   for (int r = 0; r < 16; ++r) rli[r] = __builtin_amdgcn_rcpf(li_l[crow(r, hi)]);
.LBB0_1142:
	v_exp_f32_e32 v6, v112
	v_exp_f32_e32 v7, v113
	v_exp_f32_e32 v8, v114
	v_exp_f32_e32 v9, v115
	v_exp_f32_e32 v10, v116
	v_exp_f32_e32 v11, v117
	v_exp_f32_e32 v12, v118
	v_exp_f32_e32 v13, v119
	v_exp_f32_e32 v80, v120
	v_exp_f32_e32 v81, v121
	v_exp_f32_e32 v82, v122
	v_exp_f32_e32 v83, v123
	v_exp_f32_e32 v84, v124
	v_exp_f32_e32 v85, v125
	v_exp_f32_e32 v86, v126
	v_exp_f32_e32 v87, v127
	v_exp_f32_e32 v88, v96
	v_exp_f32_e32 v89, v97
	v_exp_f32_e32 v90, v98
	v_exp_f32_e32 v91, v99
	v_exp_f32_e32 v92, v100
	v_exp_f32_e32 v93, v101
	v_exp_f32_e32 v94, v102
	v_exp_f32_e32 v95, v103
	v_exp_f32_e32 v96, v104
	v_exp_f32_e32 v97, v105
	v_exp_f32_e32 v98, v106
	v_exp_f32_e32 v99, v107
	v_exp_f32_e32 v100, v108
	v_exp_f32_e32 v102, v110
	v_exp_f32_e32 v103, v111
	v_exp_f32_e32 v101, v109
	v_pk_add_f32 v[4:5], v[98:99], v[82:83]
	v_pk_add_f32 v[104:105], v[90:91], v[8:9]
	v_pk_add_f32 v[106:107], v[102:103], v[86:87]
	v_pk_add_f32 v[108:109], v[94:95], v[12:13]
	v_pk_add_f32 v[110:111], v[96:97], v[80:81]
	v_pk_add_f32 v[112:113], v[88:89], v[6:7]
	v_pk_add_f32 v[114:115], v[100:101], v[84:85]
	v_pk_add_f32 v[116:117], v[92:93], v[10:11]
	v_pk_add_f32 v[110:111], v[112:113], v[110:111]
	v_pk_add_f32 v[114:115], v[116:117], v[114:115]
	v_pk_add_f32 v[106:107], v[108:109], v[106:107]
	v_pk_add_f32 v[4:5], v[104:105], v[4:5]
	v_pk_add_f32 v[104:105], v[110:111], v[114:115]
	v_pk_add_f32 v[4:5], v[4:5], v[106:107]
	v_cvt_pk_bf16_f32 v6, v6, v7
	v_cvt_pk_bf16_f32 v7, v8, v9
	v_cvt_pk_bf16_f32 v8, v10, v11
	v_cvt_pk_bf16_f32 v9, v12, v13
	v_cvt_pk_bf16_f32 v10, v80, v81
	s_nop 0
	v_pk_add_f32 v[4:5], v[104:105], v[4:5]
	v_cvt_pk_bf16_f32 v11, v82, v83
	v_cvt_pk_bf16_f32 v12, v84, v85
	v_cvt_pk_bf16_f32 v13, v86, v87
	v_cvt_pk_bf16_f32 v80, v88, v89
	v_cvt_pk_bf16_f32 v81, v90, v91
	s_nop 0
	v_pk_add_f32 v[4:5], v[4:5], v[4:5] op_sel:[0,1] op_sel_hi:[1,0]
	v_cvt_pk_bf16_f32 v82, v92, v93
	v_cvt_pk_bf16_f32 v83, v94, v95
	v_cvt_pk_bf16_f32 v84, v96, v97
	v_cvt_pk_bf16_f32 v85, v98, v99
	v_cvt_pk_bf16_f32 v86, v100, v101
	s_nop 0
	v_mov_b32_e32 v5, v4
	s_nop 1
	v_permlane32_swap_b32_e32 v4, v5
	v_cvt_pk_bf16_f32 v87, v102, v103
	ds_read_b64_tr_b16 v[88:89], v189 offset:0
	ds_read_b64_tr_b16 v[90:91], v189 offset:0x800
	ds_read_b64_tr_b16 v[92:93], v189 offset:0x1000
	ds_read_b64_tr_b16 v[94:95], v189 offset:0x1800
	ds_read_b64_tr_b16 v[96:97], v189 offset:0x2000
	ds_read_b64_tr_b16 v[98:99], v189 offset:0x2800
	ds_read_b64_tr_b16 v[100:101], v189 offset:0x3000
	ds_read_b64_tr_b16 v[102:103], v189 offset:0x3800
	s_waitcnt lgkmcnt(0)
	s_nop 0
	v_mfma_f32_32x32x16_bf16 v[16:31], v[6:9], v[88:91], v[16:31]
	ds_read_b64_tr_b16 v[88:89], v189 offset:0x200
	ds_read_b64_tr_b16 v[90:91], v189 offset:0xa00
	v_mfma_f32_32x32x16_bf16 v[16:31], v[10:13], v[92:95], v[16:31]
	ds_read_b64_tr_b16 v[92:93], v189 offset:0x1200
	ds_read_b64_tr_b16 v[94:95], v189 offset:0x1a00
	v_mfma_f32_32x32x16_bf16 v[16:31], v[80:83], v[96:99], v[16:31]
	ds_read_b64_tr_b16 v[96:97], v189 offset:0x2200
	ds_read_b64_tr_b16 v[98:99], v189 offset:0x2a00
	v_mfma_f32_32x32x16_bf16 v[16:31], v[84:87], v[100:103], v[16:31]
	ds_read_b64_tr_b16 v[100:101], v189 offset:0x3200
	ds_read_b64_tr_b16 v[102:103], v189 offset:0x3a00
	s_waitcnt lgkmcnt(0)
	v_mfma_f32_32x32x16_bf16 v[32:47], v[6:9], v[88:91], v[32:47]
	ds_read_b64_tr_b16 v[88:89], v189 offset:0x400
	ds_read_b64_tr_b16 v[90:91], v189 offset:0xc00
	v_mfma_f32_32x32x16_bf16 v[32:47], v[10:13], v[92:95], v[32:47]
	ds_read_b64_tr_b16 v[92:93], v189 offset:0x1400
	ds_read_b64_tr_b16 v[94:95], v189 offset:0x1c00
	v_mfma_f32_32x32x16_bf16 v[32:47], v[80:83], v[96:99], v[32:47]
	ds_read_b64_tr_b16 v[96:97], v189 offset:0x2400
	ds_read_b64_tr_b16 v[98:99], v189 offset:0x2c00
	v_mfma_f32_32x32x16_bf16 v[32:47], v[84:87], v[100:103], v[32:47]
	ds_read_b64_tr_b16 v[100:101], v189 offset:0x3400
	ds_read_b64_tr_b16 v[102:103], v189 offset:0x3c00
	s_waitcnt lgkmcnt(0)
	v_mfma_f32_32x32x16_bf16 v[48:63], v[6:9], v[88:91], v[48:63]
	ds_read_b64_tr_b16 v[88:89], v189 offset:0x600
	ds_read_b64_tr_b16 v[90:91], v189 offset:0xe00
	v_mfma_f32_32x32x16_bf16 v[48:63], v[10:13], v[92:95], v[48:63]
	ds_read_b64_tr_b16 v[92:93], v189 offset:0x1600
	ds_read_b64_tr_b16 v[94:95], v189 offset:0x1e00
	v_mfma_f32_32x32x16_bf16 v[48:63], v[80:83], v[96:99], v[48:63]
	ds_read_b64_tr_b16 v[96:97], v189 offset:0x2600
	ds_read_b64_tr_b16 v[98:99], v189 offset:0x2e00
	v_mfma_f32_32x32x16_bf16 v[48:63], v[84:87], v[100:103], v[48:63]
	ds_read_b64_tr_b16 v[100:101], v189 offset:0x3600
	ds_read_b64_tr_b16 v[102:103], v189 offset:0x3e00
	s_waitcnt lgkmcnt(0)
	v_mfma_f32_32x32x16_bf16 v[64:79], v[6:9], v[88:91], v[64:79]
	v_mfma_f32_32x32x16_bf16 v[64:79], v[10:13], v[92:95], v[64:79]
	v_mfma_f32_32x32x16_bf16 v[64:79], v[80:83], v[96:99], v[64:79]
	v_mfma_f32_32x32x16_bf16 v[64:79], v[84:87], v[100:103], v[64:79]
	s_and_saveexec_b64 s[2:3], s[0:1]
	v_add_f32_e32 v0, v2, v0
	v_fmac_f32_e32 v0, v186, v15
	v_add_f32_e32 v2, v4, v5
	v_fmac_f32_e32 v2, v0, v3
	ds_write_b32 v188, v2 offset:49152
	s_or_b64 exec, exec, s[2:3]
	s_waitcnt lgkmcnt(0)
	v_add_u32_e32 v0, s37, v156
	ds_read_b128 v[2:5], v0 offset:49152
	ds_read_b128 v[6:9], v0 offset:49184
	v_lshlrev_b32_e32 v10, 13, v185
	s_mov_b64 s[0:1], -1
	s_and_b64 vcc, exec, s[16:17]
	s_waitcnt lgkmcnt(1)
	v_rcp_f32_e32 v11, v2
	v_rcp_f32_e32 v12, v3
	v_rcp_f32_e32 v13, v4
	v_rcp_f32_e32 v14, v5
	s_waitcnt lgkmcnt(0)
	v_rcp_f32_e32 v15, v6
	ds_read_b128 v[2:5], v0 offset:49216
	v_rcp_f32_e32 v101, v7
	v_rcp_f32_e32 v102, v8
	v_rcp_f32_e32 v103, v9
	ds_read_b128 v[6:9], v0 offset:49248
	s_waitcnt lgkmcnt(1)
; __device__ __forceinline__ unsigned cvt_pk_bf16(float lo, float hi) { unsigned r; asm volatile("v_cvt_pk_bf16_f32 %0, %1, %2" : "=v"(r) : "v"(lo), "v"(hi)); return r; }
; __device__ __forceinline__ float bf1(bf16_t h) { return __uint_as_float((unsigned)h << 16); }
; __device__ __forceinline__ int crow(int r, int hi) { return (r & 3) + 8 * (r >> 2) + 4 * hi; }
; __device__ __forceinline__ void unit(const bf16* __restrict__ Qb0, const bf16* __restrict__ Kh0, const bf16* __restrict__ Vh, bf16_t* Ob, int seq, char* lds, const int tid_in, const float lam, const float onem, const float* __restrict__ subw, const float* __restrict__ kmb  ) {
;     ...
;   for (int r = 0; r < 16; ++r) rli[r] = __builtin_amdgcn_rcpf(li_l[crow(r, hi)]);
;   if (mp == 0) {
; #pragma unroll
;     for (int r = 0; r < 16; ++r)
; #pragma unroll
;       for (int d0 = 0; d0 < 4; ++d0) stage[(r * 4 + d0) * 64 + lane] = (bf16_t)(cvt_pk_bf16(o[d0][r] * rli[r], 0.f) & 0xffffu);
;   } else {
;     float ss[16];
; #pragma unroll
;     for (int r = 0; r < 16; ++r) { float q = 0.f;
; #pragma unroll
;       for (int d0 = 0; d0 < 4; ++d0) { const float a = bf1(stage[(r * 4 + d0) * 64 + lane]) - lam * bf1((bf16_t)(cvt_pk_bf16(o[d0][r] * rli[r], 0.f) & 0xffffu)); o[d0][r] = a; q += a * a; }
;       ss[r] = q; }
	v_rcp_f32_e32 v0, v2
	v_rcp_f32_e32 v2, v3
	v_rcp_f32_e32 v3, v4
	v_rcp_f32_e32 v5, v5
	s_waitcnt lgkmcnt(0)
	v_rcp_f32_e32 v6, v6
	v_rcp_f32_e32 v7, v7
	v_rcp_f32_e32 v8, v8
	v_rcp_f32_e32 v104, v9
	v_add3_u32 v4, 0, v10, v187
	v_mul_f32_e32 v100, v16, v11
	v_mul_f32_e32 v99, v32, v11
	v_mul_f32_e32 v98, v48, v11
	v_mul_f32_e32 v97, v64, v11
	v_mul_f32_e32 v96, v17, v12
	v_mul_f32_e32 v95, v33, v12
	v_mul_f32_e32 v94, v49, v12
	v_mul_f32_e32 v93, v65, v12
	v_mul_f32_e32 v92, v18, v13
	v_mul_f32_e32 v91, v34, v13
	v_mul_f32_e32 v90, v50, v13
	v_mul_f32_e32 v89, v66, v13
	v_mul_f32_e32 v88, v19, v14
	v_mul_f32_e32 v87, v35, v14
	v_mul_f32_e32 v86, v51, v14
	v_mul_f32_e32 v85, v67, v14
	v_mul_f32_e32 v84, v20, v15
	v_mul_f32_e32 v83, v36, v15
	v_mul_f32_e32 v82, v52, v15
	v_mul_f32_e32 v81, v68, v15
	v_mul_f32_e32 v80, v21, v101
	v_mul_f32_e32 v68, v37, v101
	v_mul_f32_e32 v67, v53, v101
	v_mul_f32_e32 v66, v69, v101
	v_mul_f32_e32 v65, v22, v102
	v_mul_f32_e32 v64, v38, v102
	v_mul_f32_e32 v54, v54, v102
	v_mul_f32_e32 v53, v70, v102
	v_mul_f32_e32 v52, v23, v103
	v_mul_f32_e32 v51, v39, v103
	v_mul_f32_e32 v50, v55, v103
	v_mul_f32_e32 v49, v71, v103
	v_mul_f32_e32 v48, v24, v0
	v_mul_f32_e32 v40, v40, v0
	v_mul_f32_e32 v39, v56, v0
	v_mul_f32_e32 v38, v72, v0
	v_mul_f32_e32 v37, v25, v2
	v_mul_f32_e32 v36, v41, v2
	v_mul_f32_e32 v35, v57, v2
	v_mul_f32_e32 v34, v73, v2
	v_mul_f32_e32 v33, v26, v3
	v_mul_f32_e32 v32, v42, v3
	v_mul_f32_e32 v26, v58, v3
	v_mul_f32_e32 v25, v74, v3
	v_mul_f32_e32 v24, v27, v5
	v_mul_f32_e32 v23, v43, v5
	v_mul_f32_e32 v22, v59, v5
	v_mul_f32_e32 v21, v75, v5
	v_mul_f32_e32 v20, v28, v6
	v_mul_f32_e32 v19, v44, v6
	v_mul_f32_e32 v18, v60, v6
	v_mul_f32_e32 v17, v76, v6
	v_mul_f32_e32 v16, v29, v7
	v_mul_f32_e32 v15, v45, v7
	v_mul_f32_e32 v14, v61, v7
	v_mul_f32_e32 v13, v77, v7
	v_mul_f32_e32 v12, v30, v8
	v_mul_f32_e32 v11, v46, v8
	v_mul_f32_e32 v10, v62, v8
	v_mul_f32_e32 v9, v78, v8
	v_mul_f32_e32 v8, v31, v104
	v_mul_f32_e32 v7, v47, v104
	v_mul_f32_e32 v6, v63, v104
	v_mul_f32_e32 v5, v79, v104
	s_cbranch_vccz .LBB0_1146
	ds_read_u16 v0, v4 offset:51200
	v_cvt_pk_bf16_f32 v2, v100, v1
	s_mul_hi_i32 s1, s36, 0x6800
	v_lshlrev_b32_e32 v2, 16, v2
	s_mulk_i32 s36, 0x6800
	s_waitcnt lgkmcnt(0)
	v_lshlrev_b32_e32 v0, 16, v0
	v_fma_f32 v27, -v181, v2, v0
	ds_read_u16 v0, v4 offset:51328
	v_cvt_pk_bf16_f32 v2, v99, v1
	s_add_u32 s0, s28, s36
	v_lshlrev_b32_e32 v2, 16, v2
	s_addc_u32 s1, s29, s1
	s_waitcnt lgkmcnt(0)
	v_lshlrev_b32_e32 v0, 16, v0
	v_fma_f32 v30, -v181, v2, v0
	ds_read_u16 v2, v4 offset:51456
	v_cvt_pk_bf16_f32 v3, v98, v1
	v_mul_f32_e32 v0, v30, v30
	v_lshlrev_b32_e32 v3, 16, v3
	v_fmac_f32_e32 v0, v27, v27
	s_waitcnt lgkmcnt(0)
	v_lshlrev_b32_e32 v2, 16, v2
	v_fma_f32 v44, -v181, v3, v2
	ds_read_u16 v2, v4 offset:51584
	v_cvt_pk_bf16_f32 v3, v97, v1
	v_fmac_f32_e32 v0, v44, v44
	v_lshlrev_b32_e32 v3, 16, v3
	s_waitcnt lgkmcnt(0)
	v_lshlrev_b32_e32 v2, 16, v2
	v_fma_f32 v63, -v181, v3, v2
	ds_read_u16 v2, v4 offset:51712
	v_cvt_pk_bf16_f32 v3, v96, v1
	v_fmac_f32_e32 v0, v63, v63
	v_lshlrev_b32_e32 v3, 16, v3
	s_waitcnt lgkmcnt(0)
	v_lshlrev_b32_e32 v2, 16, v2
	v_fma_f32 v28, -v181, v3, v2
	ds_read_u16 v2, v4 offset:51840
	v_cvt_pk_bf16_f32 v3, v95, v1
	s_waitcnt lgkmcnt(0)
	v_lshlrev_b32_e32 v2, 16, v2
	v_lshlrev_b32_e32 v3, 16, v3
	v_fma_f32 v41, -v181, v3, v2
	ds_read_u16 v3, v4 offset:51968
	v_cvt_pk_bf16_f32 v29, v94, v1
	v_mul_f32_e32 v2, v41, v41
	v_lshlrev_b32_e32 v29, 16, v29
	v_fmac_f32_e32 v2, v28, v28
	s_waitcnt lgkmcnt(0)
	v_lshlrev_b32_e32 v3, 16, v3
	v_fma_f32 v47, -v181, v29, v3
	ds_read_u16 v3, v4 offset:52096
	v_cvt_pk_bf16_f32 v29, v93, v1
	v_fmac_f32_e32 v2, v47, v47
	v_lshlrev_b32_e32 v29, 16, v29
	s_waitcnt lgkmcnt(0)
	v_lshlrev_b32_e32 v3, 16, v3
	v_fma_f32 v72, -v181, v29, v3
	ds_read_u16 v3, v4 offset:52224
	v_cvt_pk_bf16_f32 v29, v92, v1
	v_fmac_f32_e32 v2, v72, v72
	v_lshlrev_b32_e32 v29, 16, v29
	s_waitcnt lgkmcnt(0)
	v_lshlrev_b32_e32 v3, 16, v3
	v_fma_f32 v29, -v181, v29, v3
	ds_read_u16 v3, v4 offset:52352
	v_cvt_pk_bf16_f32 v31, v91, v1
	s_waitcnt lgkmcnt(0)
	v_lshlrev_b32_e32 v3, 16, v3
	v_lshlrev_b32_e32 v31, 16, v31
	v_fma_f32 v43, -v181, v31, v3
	ds_read_u16 v31, v4 offset:52480
	v_cvt_pk_bf16_f32 v42, v90, v1
	v_mul_f32_e32 v3, v43, v43
	v_lshlrev_b32_e32 v42, 16, v42
	v_fmac_f32_e32 v3, v29, v29
	s_waitcnt lgkmcnt(0)
	v_lshlrev_b32_e32 v31, 16, v31
	v_fma_f32 v57, -v181, v42, v31
	ds_read_u16 v31, v4 offset:52608
	v_cvt_pk_bf16_f32 v42, v89, v1
	v_fmac_f32_e32 v3, v57, v57
	v_lshlrev_b32_e32 v42, 16, v42
	s_waitcnt lgkmcnt(0)
	v_lshlrev_b32_e32 v31, 16, v31
	v_fma_f32 v76, -v181, v42, v31
	ds_read_u16 v31, v4 offset:52736
	v_cvt_pk_bf16_f32 v42, v88, v1
	v_fmac_f32_e32 v3, v76, v76
	v_lshlrev_b32_e32 v42, 16, v42
	s_waitcnt lgkmcnt(0)
	v_lshlrev_b32_e32 v31, 16, v31
	v_fma_f32 v31, -v181, v42, v31
	ds_read_u16 v42, v4 offset:52864
	v_cvt_pk_bf16_f32 v45, v87, v1
	s_waitcnt lgkmcnt(0)
	v_lshlrev_b32_e32 v42, 16, v42
	v_lshlrev_b32_e32 v45, 16, v45
	v_fma_f32 v46, -v181, v45, v42
	ds_read_u16 v42, v4 offset:52992
	v_cvt_pk_bf16_f32 v45, v86, v1
	v_mul_f32_e32 v133, v46, v46
	v_lshlrev_b32_e32 v45, 16, v45
	v_fmac_f32_e32 v133, v31, v31
	s_waitcnt lgkmcnt(0)
	v_lshlrev_b32_e32 v42, 16, v42
	v_fma_f32 v60, -v181, v45, v42
	ds_read_u16 v42, v4 offset:53120
	v_cvt_pk_bf16_f32 v45, v85, v1
	v_fmac_f32_e32 v133, v60, v60
	v_lshlrev_b32_e32 v45, 16, v45
	s_waitcnt lgkmcnt(0)
	v_lshlrev_b32_e32 v42, 16, v42
	v_fma_f32 v101, -v181, v45, v42
	ds_read_u16 v42, v4 offset:53248
	v_cvt_pk_bf16_f32 v45, v84, v1
	v_fmac_f32_e32 v133, v101, v101
	v_lshlrev_b32_e32 v45, 16, v45
	s_waitcnt lgkmcnt(0)
; __device__ __forceinline__ unsigned cvt_pk_bf16(float lo, float hi) { unsigned r; asm volatile("v_cvt_pk_bf16_f32 %0, %1, %2" : "=v"(r) : "v"(lo), "v"(hi)); return r; }
; __device__ __forceinline__ float bf1(bf16_t h) { return __uint_as_float((unsigned)h << 16); }
; __device__ __forceinline__ void unit(const bf16* __restrict__ Qb0, const bf16* __restrict__ Kh0, const bf16* __restrict__ Vh, bf16_t* Ob, int seq, char* lds, const int tid_in, const float lam, const float onem, const float* __restrict__ subw, const float* __restrict__ kmb  ) {
;     ...
;     for (int r = 0; r < 16; ++r) { float q = 0.f;
; #pragma unroll
;       for (int d0 = 0; d0 < 4; ++d0) { const float a = bf1(stage[(r * 4 + d0) * 64 + lane]) - lam * bf1((bf16_t)(cvt_pk_bf16(o[d0][r] * rli[r], 0.f) & 0xffffu)); o[d0][r] = a; q += a * a; }
;       ss[r] = q; }
	v_lshlrev_b32_e32 v42, 16, v42
	v_fma_f32 v42, -v181, v45, v42
	ds_read_u16 v45, v4 offset:53376
	v_cvt_pk_bf16_f32 v55, v83, v1
	s_waitcnt lgkmcnt(0)
	v_lshlrev_b32_e32 v45, 16, v45
	v_lshlrev_b32_e32 v55, 16, v55
	v_fma_f32 v56, -v181, v55, v45
	ds_read_u16 v45, v4 offset:53504
	v_cvt_pk_bf16_f32 v55, v82, v1
	v_mul_f32_e32 v134, v56, v56
	v_lshlrev_b32_e32 v55, 16, v55
	v_fmac_f32_e32 v134, v42, v42
	s_waitcnt lgkmcnt(0)
	v_lshlrev_b32_e32 v45, 16, v45
	v_fma_f32 v69, -v181, v55, v45
	ds_read_u16 v45, v4 offset:53632
	v_cvt_pk_bf16_f32 v55, v81, v1
	v_fmac_f32_e32 v134, v69, v69
	v_lshlrev_b32_e32 v55, 16, v55
	s_waitcnt lgkmcnt(0)
	v_lshlrev_b32_e32 v45, 16, v45
	v_fma_f32 v105, -v181, v55, v45
	ds_read_u16 v45, v4 offset:53760
	v_cvt_pk_bf16_f32 v55, v80, v1
	v_fmac_f32_e32 v134, v105, v105
	v_lshlrev_b32_e32 v55, 16, v55
	s_waitcnt lgkmcnt(0)
	v_lshlrev_b32_e32 v45, 16, v45
	v_fma_f32 v45, -v181, v55, v45
	ds_read_u16 v55, v4 offset:53888
	v_cvt_pk_bf16_f32 v58, v68, v1
	s_waitcnt lgkmcnt(0)
	v_lshlrev_b32_e32 v55, 16, v55
	v_lshlrev_b32_e32 v58, 16, v58
	v_fma_f32 v59, -v181, v58, v55
	ds_read_u16 v55, v4 offset:54016
	v_cvt_pk_bf16_f32 v58, v67, v1
	v_mul_f32_e32 v135, v59, v59
	v_lshlrev_b32_e32 v58, 16, v58
	v_fmac_f32_e32 v135, v45, v45
	s_waitcnt lgkmcnt(0)
	v_lshlrev_b32_e32 v55, 16, v55
	v_fma_f32 v73, -v181, v58, v55
	ds_read_u16 v55, v4 offset:54144
	v_cvt_pk_bf16_f32 v58, v66, v1
	v_fmac_f32_e32 v135, v73, v73
	v_lshlrev_b32_e32 v58, 16, v58
	s_waitcnt lgkmcnt(0)
	v_lshlrev_b32_e32 v55, 16, v55
	v_fma_f32 v109, -v181, v58, v55
	ds_read_u16 v55, v4 offset:54272
	v_cvt_pk_bf16_f32 v58, v65, v1
	v_fmac_f32_e32 v135, v109, v109
	v_lshlrev_b32_e32 v58, 16, v58
	s_waitcnt lgkmcnt(0)
	v_lshlrev_b32_e32 v55, 16, v55
	v_fma_f32 v55, -v181, v58, v55
	ds_read_u16 v58, v4 offset:54400
	v_cvt_pk_bf16_f32 v61, v64, v1
	s_waitcnt lgkmcnt(0)
	v_lshlrev_b32_e32 v58, 16, v58
	v_lshlrev_b32_e32 v61, 16, v61
	v_fma_f32 v62, -v181, v61, v58
	ds_read_u16 v58, v4 offset:54528
	v_cvt_pk_bf16_f32 v61, v54, v1
	v_mul_f32_e32 v136, v62, v62
	v_lshlrev_b32_e32 v61, 16, v61
	v_fmac_f32_e32 v136, v55, v55
	s_waitcnt lgkmcnt(0)
	v_lshlrev_b32_e32 v58, 16, v58
	v_fma_f32 v77, -v181, v61, v58
	ds_read_u16 v58, v4 offset:54656
	v_cvt_pk_bf16_f32 v61, v53, v1
	v_fmac_f32_e32 v136, v77, v77
	v_lshlrev_b32_e32 v61, 16, v61
	s_waitcnt lgkmcnt(0)
	v_lshlrev_b32_e32 v58, 16, v58
	v_fma_f32 v113, -v181, v61, v58
	ds_read_u16 v58, v4 offset:54784
	v_cvt_pk_bf16_f32 v61, v52, v1
	v_fmac_f32_e32 v136, v113, v113
	v_lshlrev_b32_e32 v61, 16, v61
	s_waitcnt lgkmcnt(0)
	v_lshlrev_b32_e32 v58, 16, v58
	v_fma_f32 v58, -v181, v61, v58
	ds_read_u16 v61, v4 offset:54912
	v_cvt_pk_bf16_f32 v70, v51, v1
	s_waitcnt lgkmcnt(0)
	v_lshlrev_b32_e32 v61, 16, v61
	v_lshlrev_b32_e32 v70, 16, v70
	v_fma_f32 v71, -v181, v70, v61
	ds_read_u16 v61, v4 offset:55040
	v_cvt_pk_bf16_f32 v70, v50, v1
	v_mul_f32_e32 v137, v71, v71
	v_lshlrev_b32_e32 v70, 16, v70
	v_fmac_f32_e32 v137, v58, v58
	s_waitcnt lgkmcnt(0)
	v_lshlrev_b32_e32 v61, 16, v61
	v_fma_f32 v102, -v181, v70, v61
	ds_read_u16 v61, v4 offset:55168
	v_cvt_pk_bf16_f32 v70, v49, v1
	v_fmac_f32_e32 v137, v102, v102
	v_lshlrev_b32_e32 v70, 16, v70
	s_waitcnt lgkmcnt(0)
	v_lshlrev_b32_e32 v61, 16, v61
	v_fma_f32 v117, -v181, v70, v61
	ds_read_u16 v61, v4 offset:55296
	v_cvt_pk_bf16_f32 v70, v48, v1
	v_fmac_f32_e32 v137, v117, v117
	v_lshlrev_b32_e32 v70, 16, v70
	s_waitcnt lgkmcnt(0)
	v_lshlrev_b32_e32 v61, 16, v61
	v_fma_f32 v61, -v181, v70, v61
	ds_read_u16 v70, v4 offset:55424
	v_cvt_pk_bf16_f32 v74, v40, v1
	s_waitcnt lgkmcnt(0)
	v_lshlrev_b32_e32 v70, 16, v70
	v_lshlrev_b32_e32 v74, 16, v74
	v_fma_f32 v75, -v181, v74, v70
	ds_read_u16 v70, v4 offset:55552
	v_cvt_pk_bf16_f32 v74, v39, v1
	v_mul_f32_e32 v138, v75, v75
	v_lshlrev_b32_e32 v74, 16, v74
	v_fmac_f32_e32 v138, v61, v61
	s_waitcnt lgkmcnt(0)
	v_lshlrev_b32_e32 v70, 16, v70
	v_fma_f32 v106, -v181, v74, v70
	ds_read_u16 v70, v4 offset:55680
	v_cvt_pk_bf16_f32 v74, v38, v1
	v_fmac_f32_e32 v138, v106, v106
	v_lshlrev_b32_e32 v74, 16, v74
	s_waitcnt lgkmcnt(0)
	v_lshlrev_b32_e32 v70, 16, v70
	v_fma_f32 v120, -v181, v74, v70
	ds_read_u16 v70, v4 offset:55808
	v_cvt_pk_bf16_f32 v74, v37, v1
	v_fmac_f32_e32 v138, v120, v120
	v_lshlrev_b32_e32 v74, 16, v74
	s_waitcnt lgkmcnt(0)
	v_lshlrev_b32_e32 v70, 16, v70
	v_fma_f32 v70, -v181, v74, v70
	ds_read_u16 v74, v4 offset:55936
	v_cvt_pk_bf16_f32 v78, v36, v1
	s_waitcnt lgkmcnt(0)
	v_lshlrev_b32_e32 v74, 16, v74
	v_lshlrev_b32_e32 v78, 16, v78
	v_fma_f32 v79, -v181, v78, v74
	ds_read_u16 v74, v4 offset:56064
	v_cvt_pk_bf16_f32 v78, v35, v1
	v_mul_f32_e32 v139, v79, v79
	v_lshlrev_b32_e32 v78, 16, v78
	v_fmac_f32_e32 v139, v70, v70
	s_waitcnt lgkmcnt(0)
	v_lshlrev_b32_e32 v74, 16, v74
	v_fma_f32 v110, -v181, v78, v74
	ds_read_u16 v74, v4 offset:56192
	v_cvt_pk_bf16_f32 v78, v34, v1
	v_fmac_f32_e32 v139, v110, v110
	v_lshlrev_b32_e32 v78, 16, v78
	s_waitcnt lgkmcnt(0)
	v_lshlrev_b32_e32 v74, 16, v74
	v_fma_f32 v123, -v181, v78, v74
	ds_read_u16 v74, v4 offset:56320
	v_cvt_pk_bf16_f32 v78, v33, v1
	v_fmac_f32_e32 v139, v123, v123
	v_lshlrev_b32_e32 v78, 16, v78
	s_waitcnt lgkmcnt(0)
	v_lshlrev_b32_e32 v74, 16, v74
	v_fma_f32 v74, -v181, v78, v74
	ds_read_u16 v78, v4 offset:56448
	v_cvt_pk_bf16_f32 v103, v32, v1
	s_waitcnt lgkmcnt(0)
	v_lshlrev_b32_e32 v78, 16, v78
	v_lshlrev_b32_e32 v103, 16, v103
	v_fma_f32 v104, -v181, v103, v78
	ds_read_u16 v78, v4 offset:56576
	v_cvt_pk_bf16_f32 v103, v26, v1
	v_mul_f32_e32 v140, v104, v104
	v_lshlrev_b32_e32 v103, 16, v103
	v_fmac_f32_e32 v140, v74, v74
	s_waitcnt lgkmcnt(0)
; __device__ __forceinline__ void unit(const bf16* __restrict__ Qb0, const bf16* __restrict__ Kh0, const bf16* __restrict__ Vh, bf16_t* Ob, int seq, char* lds, const int tid_in, const float lam, const float onem, const float* __restrict__ subw, const float* __restrict__ kmb  ) {
;     ...
; #pragma unroll
;     for (int m = 1; m < 32; m <<= 1)
; #pragma unroll
;       for (int r = 0; r < 16; ++r) ss[r] += __int_as_float(__builtin_amdgcn_ds_bpermute((lane ^ m) << 2, __float_as_int(ss[r])));
	v_lshlrev_b32_e32 v78, 16, v78
	v_fma_f32 v114, -v181, v103, v78
	ds_read_u16 v78, v4 offset:56704
	v_cvt_pk_bf16_f32 v103, v25, v1
	v_fmac_f32_e32 v140, v114, v114
	v_lshlrev_b32_e32 v103, 16, v103
	s_waitcnt lgkmcnt(0)
	v_lshlrev_b32_e32 v78, 16, v78
	v_fma_f32 v125, -v181, v103, v78
	ds_read_u16 v78, v4 offset:56832
	v_cvt_pk_bf16_f32 v103, v24, v1
	v_fmac_f32_e32 v140, v125, v125
	v_lshlrev_b32_e32 v103, 16, v103
	s_waitcnt lgkmcnt(0)
	v_lshlrev_b32_e32 v78, 16, v78
	v_fma_f32 v78, -v181, v103, v78
	ds_read_u16 v103, v4 offset:56960
	v_cvt_pk_bf16_f32 v107, v23, v1
	s_waitcnt lgkmcnt(0)
	v_lshlrev_b32_e32 v103, 16, v103
	v_lshlrev_b32_e32 v107, 16, v107
	v_fma_f32 v108, -v181, v107, v103
	ds_read_u16 v103, v4 offset:57088
	v_cvt_pk_bf16_f32 v107, v22, v1
	v_mul_f32_e32 v141, v108, v108
	v_lshlrev_b32_e32 v107, 16, v107
	v_fmac_f32_e32 v141, v78, v78
	s_waitcnt lgkmcnt(0)
	v_lshlrev_b32_e32 v103, 16, v103
	v_fma_f32 v118, -v181, v107, v103
	ds_read_u16 v103, v4 offset:57216
	v_cvt_pk_bf16_f32 v107, v21, v1
	v_fmac_f32_e32 v141, v118, v118
	v_lshlrev_b32_e32 v107, 16, v107
	s_waitcnt lgkmcnt(0)
	v_lshlrev_b32_e32 v103, 16, v103
	v_fma_f32 v127, -v181, v107, v103
	ds_read_u16 v103, v4 offset:57344
	v_cvt_pk_bf16_f32 v107, v20, v1
	v_fmac_f32_e32 v141, v127, v127
	v_lshlrev_b32_e32 v107, 16, v107
	s_waitcnt lgkmcnt(0)
	v_lshlrev_b32_e32 v103, 16, v103
	v_fma_f32 v103, -v181, v107, v103
	ds_read_u16 v107, v4 offset:57472
	v_cvt_pk_bf16_f32 v111, v19, v1
	s_waitcnt lgkmcnt(0)
	v_lshlrev_b32_e32 v107, 16, v107
	v_lshlrev_b32_e32 v111, 16, v111
	v_fma_f32 v112, -v181, v111, v107
	ds_read_u16 v107, v4 offset:57600
	v_cvt_pk_bf16_f32 v111, v18, v1
	v_mul_f32_e32 v142, v112, v112
	v_lshlrev_b32_e32 v111, 16, v111
	v_fmac_f32_e32 v142, v103, v103
	s_waitcnt lgkmcnt(0)
	v_lshlrev_b32_e32 v107, 16, v107
	v_fma_f32 v121, -v181, v111, v107
	ds_read_u16 v107, v4 offset:57728
	v_cvt_pk_bf16_f32 v111, v17, v1
	v_fmac_f32_e32 v142, v121, v121
	v_lshlrev_b32_e32 v111, 16, v111
	s_waitcnt lgkmcnt(0)
	v_lshlrev_b32_e32 v107, 16, v107
	v_fma_f32 v129, -v181, v111, v107
	ds_read_u16 v107, v4 offset:57856
	v_cvt_pk_bf16_f32 v111, v16, v1
	v_fmac_f32_e32 v142, v129, v129
	v_lshlrev_b32_e32 v111, 16, v111
	s_waitcnt lgkmcnt(0)
	v_lshlrev_b32_e32 v107, 16, v107
	v_fma_f32 v107, -v181, v111, v107
	ds_read_u16 v111, v4 offset:57984
	v_cvt_pk_bf16_f32 v115, v15, v1
	s_waitcnt lgkmcnt(0)
	v_lshlrev_b32_e32 v111, 16, v111
	v_lshlrev_b32_e32 v115, 16, v115
	v_fma_f32 v116, -v181, v115, v111
	ds_read_u16 v111, v4 offset:58112
	v_cvt_pk_bf16_f32 v115, v14, v1
	v_mul_f32_e32 v143, v116, v116
	v_lshlrev_b32_e32 v115, 16, v115
	v_fmac_f32_e32 v143, v107, v107
	s_waitcnt lgkmcnt(0)
	v_lshlrev_b32_e32 v111, 16, v111
	v_fma_f32 v124, -v181, v115, v111
	ds_read_u16 v111, v4 offset:58240
	v_cvt_pk_bf16_f32 v115, v13, v1
	v_fmac_f32_e32 v143, v124, v124
	v_lshlrev_b32_e32 v115, 16, v115
	s_waitcnt lgkmcnt(0)
	v_lshlrev_b32_e32 v111, 16, v111
	v_fma_f32 v130, -v181, v115, v111
	ds_read_u16 v111, v4 offset:58368
	v_cvt_pk_bf16_f32 v115, v12, v1
	v_fmac_f32_e32 v143, v130, v130
	v_lshlrev_b32_e32 v115, 16, v115
	s_waitcnt lgkmcnt(0)
	v_lshlrev_b32_e32 v111, 16, v111
	v_fma_f32 v111, -v181, v115, v111
	ds_read_u16 v115, v4 offset:58496
	v_cvt_pk_bf16_f32 v119, v11, v1
	s_waitcnt lgkmcnt(0)
	v_lshlrev_b32_e32 v115, 16, v115
	v_lshlrev_b32_e32 v119, 16, v119
	v_fma_f32 v119, -v181, v119, v115
	ds_read_u16 v115, v4 offset:58624
	v_cvt_pk_bf16_f32 v122, v10, v1
	v_mul_f32_e32 v144, v119, v119
	v_lshlrev_b32_e32 v122, 16, v122
	v_fmac_f32_e32 v144, v111, v111
	s_waitcnt lgkmcnt(0)
	v_lshlrev_b32_e32 v115, 16, v115
	v_fma_f32 v126, -v181, v122, v115
	ds_read_u16 v115, v4 offset:58752
	v_cvt_pk_bf16_f32 v122, v9, v1
	v_fmac_f32_e32 v144, v126, v126
	v_lshlrev_b32_e32 v122, 16, v122
	s_waitcnt lgkmcnt(0)
	v_lshlrev_b32_e32 v115, 16, v115
	v_fma_f32 v131, -v181, v122, v115
	ds_read_u16 v115, v4 offset:58880
	v_cvt_pk_bf16_f32 v122, v8, v1
	v_fmac_f32_e32 v144, v131, v131
	v_lshlrev_b32_e32 v122, 16, v122
	s_waitcnt lgkmcnt(0)
	v_lshlrev_b32_e32 v115, 16, v115
	v_fma_f32 v115, -v181, v122, v115
	ds_read_u16 v122, v4 offset:59008
	v_cvt_pk_bf16_f32 v128, v7, v1
	s_waitcnt lgkmcnt(0)
	v_lshlrev_b32_e32 v122, 16, v122
	v_lshlrev_b32_e32 v128, 16, v128
	v_fma_f32 v122, -v181, v128, v122
	ds_read_u16 v128, v4 offset:59136
	v_cvt_pk_bf16_f32 v132, v6, v1
	v_mul_f32_e32 v145, v122, v122
	v_lshlrev_b32_e32 v132, 16, v132
	v_fmac_f32_e32 v145, v115, v115
	s_waitcnt lgkmcnt(0)
	v_lshlrev_b32_e32 v128, 16, v128
	v_fma_f32 v128, -v181, v132, v128
	ds_read_u16 v132, v4 offset:59264
	v_cvt_pk_bf16_f32 v146, v5, v1
	v_fmac_f32_e32 v145, v128, v128
	v_lshlrev_b32_e32 v146, 16, v146
	s_waitcnt lgkmcnt(0)
	v_lshlrev_b32_e32 v132, 16, v132
	v_fma_f32 v132, -v181, v146, v132
	v_lshlrev_b32_e32 v146, 2, v157
	v_fmac_f32_e32 v145, v132, v132
	v_xor_b32_e32 v156, 64, v146
	v_xor_b32_e32 v147, 4, v146
	ds_bpermute_b32 v232, v147, v0
	ds_bpermute_b32 v233, v147, v2
	ds_bpermute_b32 v234, v147, v3
	ds_bpermute_b32 v235, v147, v133
	ds_bpermute_b32 v236, v147, v134
	ds_bpermute_b32 v237, v147, v135
	ds_bpermute_b32 v238, v147, v136
	ds_bpermute_b32 v239, v147, v137
	ds_bpermute_b32 v240, v147, v138
	ds_bpermute_b32 v241, v147, v139
	ds_bpermute_b32 v242, v147, v140
	ds_bpermute_b32 v243, v147, v141
	ds_bpermute_b32 v244, v147, v142
	ds_bpermute_b32 v245, v147, v143
	ds_bpermute_b32 v246, v147, v144
	ds_bpermute_b32 v247, v147, v145
	s_waitcnt lgkmcnt(15)
	v_add_f32_e32 v0, v0, v232
	s_waitcnt lgkmcnt(14)
	v_add_f32_e32 v2, v2, v233
	s_waitcnt lgkmcnt(13)
	v_add_f32_e32 v3, v3, v234
	s_waitcnt lgkmcnt(12)
; __device__ __forceinline__ void unit(const bf16* __restrict__ Qb0, const bf16* __restrict__ Kh0, const bf16* __restrict__ Vh, bf16_t* Ob, int seq, char* lds, const int tid_in, const float lam, const float onem, const float* __restrict__ subw, const float* __restrict__ kmb  ) {
;     ...
; #pragma unroll
;     for (int m = 1; m < 32; m <<= 1)
; #pragma unroll
;       for (int r = 0; r < 16; ++r) ss[r] += __int_as_float(__builtin_amdgcn_ds_bpermute((lane ^ m) << 2, __float_as_int(ss[r])));
	v_add_f32_e32 v133, v133, v235
	s_waitcnt lgkmcnt(11)
	v_add_f32_e32 v134, v134, v236
	s_waitcnt lgkmcnt(10)
	v_add_f32_e32 v135, v135, v237
	s_waitcnt lgkmcnt(9)
	v_add_f32_e32 v136, v136, v238
	s_waitcnt lgkmcnt(8)
	v_add_f32_e32 v137, v137, v239
	s_waitcnt lgkmcnt(7)
	v_add_f32_e32 v138, v138, v240
	s_waitcnt lgkmcnt(6)
	v_add_f32_e32 v139, v139, v241
	s_waitcnt lgkmcnt(5)
	v_add_f32_e32 v140, v140, v242
	s_waitcnt lgkmcnt(4)
	v_add_f32_e32 v141, v141, v243
	s_waitcnt lgkmcnt(3)
	v_add_f32_e32 v142, v142, v244
	s_waitcnt lgkmcnt(2)
	v_add_f32_e32 v143, v143, v245
	s_waitcnt lgkmcnt(1)
	v_add_f32_e32 v144, v144, v246
	s_waitcnt lgkmcnt(0)
	v_add_f32_e32 v145, v145, v247
	v_xor_b32_e32 v147, 8, v146
	ds_bpermute_b32 v232, v147, v0
	ds_bpermute_b32 v233, v147, v2
	ds_bpermute_b32 v234, v147, v3
	ds_bpermute_b32 v235, v147, v133
	ds_bpermute_b32 v236, v147, v134
	ds_bpermute_b32 v237, v147, v135
	ds_bpermute_b32 v238, v147, v136
	ds_bpermute_b32 v239, v147, v137
	ds_bpermute_b32 v240, v147, v138
	ds_bpermute_b32 v241, v147, v139
	ds_bpermute_b32 v242, v147, v140
	ds_bpermute_b32 v243, v147, v141
	ds_bpermute_b32 v244, v147, v142
	ds_bpermute_b32 v245, v147, v143
	ds_bpermute_b32 v246, v147, v144
	ds_bpermute_b32 v247, v147, v145
	s_waitcnt lgkmcnt(15)
	v_add_f32_e32 v0, v0, v232
	s_waitcnt lgkmcnt(14)
	v_add_f32_e32 v2, v2, v233
	s_waitcnt lgkmcnt(13)
	v_add_f32_e32 v3, v3, v234
	s_waitcnt lgkmcnt(12)
	v_add_f32_e32 v133, v133, v235
	s_waitcnt lgkmcnt(11)
	v_add_f32_e32 v134, v134, v236
	s_waitcnt lgkmcnt(10)
	v_add_f32_e32 v135, v135, v237
	s_waitcnt lgkmcnt(9)
	v_add_f32_e32 v136, v136, v238
	s_waitcnt lgkmcnt(8)
	v_add_f32_e32 v137, v137, v239
	s_waitcnt lgkmcnt(7)
	v_add_f32_e32 v138, v138, v240
	s_waitcnt lgkmcnt(6)
	v_add_f32_e32 v139, v139, v241
	s_waitcnt lgkmcnt(5)
	v_add_f32_e32 v140, v140, v242
	s_waitcnt lgkmcnt(4)
	v_add_f32_e32 v141, v141, v243
	s_waitcnt lgkmcnt(3)
	v_add_f32_e32 v142, v142, v244
	s_waitcnt lgkmcnt(2)
	v_add_f32_e32 v143, v143, v245
	s_waitcnt lgkmcnt(1)
	v_add_f32_e32 v144, v144, v246
	s_waitcnt lgkmcnt(0)
	v_add_f32_e32 v145, v145, v247
	v_xor_b32_e32 v147, 16, v146
	ds_bpermute_b32 v232, v147, v0
	ds_bpermute_b32 v233, v147, v2
	ds_bpermute_b32 v234, v147, v3
	ds_bpermute_b32 v235, v147, v133
	ds_bpermute_b32 v236, v147, v134
	ds_bpermute_b32 v237, v147, v135
	ds_bpermute_b32 v238, v147, v136
	ds_bpermute_b32 v239, v147, v137
	ds_bpermute_b32 v240, v147, v138
	ds_bpermute_b32 v241, v147, v139
	ds_bpermute_b32 v242, v147, v140
	ds_bpermute_b32 v243, v147, v141
	ds_bpermute_b32 v244, v147, v142
	ds_bpermute_b32 v245, v147, v143
	ds_bpermute_b32 v246, v147, v144
	ds_bpermute_b32 v247, v147, v145
	s_waitcnt lgkmcnt(15)
	v_add_f32_e32 v0, v0, v232
	s_waitcnt lgkmcnt(14)
	v_add_f32_e32 v2, v2, v233
	s_waitcnt lgkmcnt(13)
	v_add_f32_e32 v3, v3, v234
	s_waitcnt lgkmcnt(12)
	v_add_f32_e32 v133, v133, v235
	s_waitcnt lgkmcnt(11)
	v_add_f32_e32 v134, v134, v236
	s_waitcnt lgkmcnt(10)
	v_add_f32_e32 v135, v135, v237
	s_waitcnt lgkmcnt(9)
	v_add_f32_e32 v136, v136, v238
	s_waitcnt lgkmcnt(8)
	v_add_f32_e32 v137, v137, v239
	s_waitcnt lgkmcnt(7)
	v_add_f32_e32 v138, v138, v240
	s_waitcnt lgkmcnt(6)
	v_add_f32_e32 v139, v139, v241
	s_waitcnt lgkmcnt(5)
	v_add_f32_e32 v140, v140, v242
	s_waitcnt lgkmcnt(4)
	v_add_f32_e32 v141, v141, v243
	s_waitcnt lgkmcnt(3)
	v_add_f32_e32 v142, v142, v244
	s_waitcnt lgkmcnt(2)
	v_add_f32_e32 v143, v143, v245
	s_waitcnt lgkmcnt(1)
	v_add_f32_e32 v144, v144, v246
	s_waitcnt lgkmcnt(0)
	v_add_f32_e32 v145, v145, v247
	v_xor_b32_e32 v147, 32, v146
	ds_bpermute_b32 v232, v147, v0
	ds_bpermute_b32 v233, v147, v2
	ds_bpermute_b32 v234, v147, v3
	ds_bpermute_b32 v235, v147, v133
	ds_bpermute_b32 v236, v147, v134
	ds_bpermute_b32 v237, v147, v135
	ds_bpermute_b32 v238, v147, v136
	ds_bpermute_b32 v239, v147, v137
	ds_bpermute_b32 v240, v147, v138
	ds_bpermute_b32 v241, v147, v139
	ds_bpermute_b32 v242, v147, v140
	ds_bpermute_b32 v243, v147, v141
	ds_bpermute_b32 v244, v147, v142
	ds_bpermute_b32 v245, v147, v143
	ds_bpermute_b32 v246, v147, v144
	ds_bpermute_b32 v247, v147, v145
	s_waitcnt lgkmcnt(15)
	v_add_f32_e32 v0, v0, v232
	s_waitcnt lgkmcnt(14)
	v_add_f32_e32 v148, v2, v233
	s_waitcnt lgkmcnt(13)
	v_add_f32_e32 v3, v3, v234
	s_waitcnt lgkmcnt(12)
	v_add_f32_e32 v133, v133, v235
	s_waitcnt lgkmcnt(11)
	v_add_f32_e32 v134, v134, v236
	s_waitcnt lgkmcnt(10)
	v_add_f32_e32 v135, v135, v237
	s_waitcnt lgkmcnt(9)
	v_add_f32_e32 v136, v136, v238
	s_waitcnt lgkmcnt(8)
	v_add_f32_e32 v137, v137, v239
	s_waitcnt lgkmcnt(7)
	v_add_f32_e32 v138, v138, v240
	s_waitcnt lgkmcnt(6)
	v_add_f32_e32 v139, v139, v241
	s_waitcnt lgkmcnt(5)
	v_add_f32_e32 v140, v140, v242
	s_waitcnt lgkmcnt(4)
	v_add_f32_e32 v152, v141, v243
	s_waitcnt lgkmcnt(3)
	v_add_f32_e32 v142, v142, v244
	s_waitcnt lgkmcnt(2)
	v_add_f32_e32 v153, v143, v245
	s_waitcnt lgkmcnt(1)
	v_add_f32_e32 v154, v144, v246
	s_waitcnt lgkmcnt(0)
	v_add_f32_e32 v155, v145, v247
	ds_bpermute_b32 v232, v156, v0
	ds_bpermute_b32 v233, v156, v148
	ds_bpermute_b32 v234, v156, v3
	ds_bpermute_b32 v235, v156, v133
	ds_bpermute_b32 v236, v156, v134
	ds_bpermute_b32 v237, v156, v135
	ds_bpermute_b32 v238, v156, v136
	ds_bpermute_b32 v239, v156, v137
	ds_bpermute_b32 v240, v156, v138
	ds_bpermute_b32 v241, v156, v139
	ds_bpermute_b32 v242, v156, v140
	ds_bpermute_b32 v243, v156, v152
	ds_bpermute_b32 v244, v156, v142
	ds_bpermute_b32 v245, v156, v153
	ds_bpermute_b32 v246, v156, v154
	ds_bpermute_b32 v247, v156, v155
	s_waitcnt lgkmcnt(15)
	v_add_f32_e32 v2, v0, v232
	s_waitcnt lgkmcnt(14)
	v_add_f32_e32 v151, v148, v233
	s_waitcnt lgkmcnt(13)
; __device__ __forceinline__ unsigned cvt_pk_bf16(float lo, float hi) { unsigned r; asm volatile("v_cvt_pk_bf16_f32 %0, %1, %2" : "=v"(r) : "v"(lo), "v"(hi)); return r; }
; __device__ __forceinline__ int crow(int r, int hi) { return (r & 3) + 8 * (r >> 2) + 4 * hi; }
; __device__ __forceinline__ void unit(const bf16* __restrict__ Qb0, const bf16* __restrict__ Kh0, const bf16* __restrict__ Vh, bf16_t* Ob, int seq, char* lds, const int tid_in, const float lam, const float onem, const float* __restrict__ subw, const float* __restrict__ kmb  ) {
;     ...
; #pragma unroll
;     for (int m = 1; m < 32; m <<= 1)
; #pragma unroll
;       for (int r = 0; r < 16; ++r) ss[r] += __int_as_float(__builtin_amdgcn_ds_bpermute((lane ^ m) << 2, __float_as_int(ss[r])));
;     float sw[4];
; #pragma unroll
;     for (int d0 = 0; d0 < 4; ++d0) sw[d0] = subw[d0 * 32 + r32] * onem;
;     bf16_t* Ow = Ob + (long)(wid * QBLK) * LDOB;
; #pragma unroll
;     for (int r = 0; r < 16; ++r) { const int orow = crow(r, hi); const float rs = 1.0f / sqrtf(ss[r] * (1.f / 128.f) + RMS_EPS);
; #pragma unroll
;       for (int d0 = 0; d0 < 4; ++d0) Ow[(long)orow * LDOB + d0 * 32 + r32] = (bf16_t)(cvt_pk_bf16(o[d0][r] * rs * sw[d0], 0.f) & 0xffffu); }
	v_add_f32_e32 v150, v3, v234
	s_waitcnt lgkmcnt(12)
	v_add_f32_e32 v149, v133, v235
	s_waitcnt lgkmcnt(11)
	v_add_f32_e32 v148, v134, v236
	s_waitcnt lgkmcnt(10)
	v_add_f32_e32 v147, v135, v237
	s_waitcnt lgkmcnt(9)
	v_add_f32_e32 v146, v136, v238
	s_waitcnt lgkmcnt(8)
	v_add_f32_e32 v145, v137, v239
	s_waitcnt lgkmcnt(7)
	v_add_f32_e32 v144, v138, v240
	s_waitcnt lgkmcnt(6)
	v_add_f32_e32 v143, v139, v241
	s_waitcnt lgkmcnt(5)
	v_add_f32_e32 v141, v140, v242
	s_waitcnt lgkmcnt(4)
	v_add_f32_e32 v140, v152, v243
	s_waitcnt lgkmcnt(3)
	v_add_f32_e32 v139, v142, v244
	s_waitcnt lgkmcnt(2)
	v_add_f32_e32 v135, v153, v245
	s_waitcnt lgkmcnt(1)
	v_add_f32_e32 v134, v154, v246
	s_waitcnt lgkmcnt(0)
	v_add_f32_e32 v133, v155, v247
	v_lshlrev_b32_e32 v0, 2, v184
	global_load_dword v232, v0, s[12:13]
	global_load_dword v233, v0, s[12:13] offset:128
	global_load_dword v234, v0, s[12:13] offset:256
	global_load_dword v235, v0, s[12:13] offset:384
	s_waitcnt vmcnt(0)
	v_mul_f32_e32 v138, v182, v232
	v_mul_f32_e32 v136, v182, v233
	v_mul_f32_e32 v137, v182, v234
	v_mul_f32_e32 v142, v182, v235
	v_lshlrev_b32_e32 v0, 1, v184
	v_lshl_add_u64 v[152:153], s[0:1], 0, v[0:1]
	v_fmamk_f32 v0, v2, 0x3c000000, v219
	v_cmp_gt_f32_e32 vcc, s75, v0
	v_mul_f32_e32 v2, 0x4f800000, v0
	s_nop 0
	v_cndmask_b32_e32 v0, v0, v2, vcc
	v_sqrt_f32_e32 v2, v0
	s_nop 0
	v_add_u32_e32 v3, -1, v2
	v_fma_f32 v154, -v3, v2, v0
	v_cmp_ge_f32_e64 s[0:1], 0, v154
	v_add_u32_e32 v154, 1, v2
	s_nop 0
	v_cndmask_b32_e64 v3, v2, v3, s[0:1]
	v_fma_f32 v2, -v154, v2, v0
	v_cmp_lt_f32_e64 s[0:1], 0, v2
	s_nop 1
	v_cndmask_b32_e64 v2, v3, v154, s[0:1]
	v_mul_f32_e32 v3, 0x37800000, v2
	v_cndmask_b32_e32 v2, v2, v3, vcc
	v_cmp_class_f32_e32 vcc, v0, v220
	s_nop 1
	v_cndmask_b32_e32 v0, v2, v0, vcc
	v_div_scale_f32 v2, s[0:1], v0, v0, 1.0
	v_rcp_f32_e32 v3, v2
	s_nop 0
	v_fma_f32 v154, -v2, v3, 1.0
	v_fmac_f32_e32 v3, v154, v3
	v_div_scale_f32 v154, vcc, 1.0, v0, 1.0
	v_mul_f32_e32 v155, v154, v3
	v_fma_f32 v156, -v2, v155, v154
	v_fmac_f32_e32 v155, v156, v3
	v_fma_f32 v2, -v2, v155, v154
	v_div_fmas_f32 v2, v2, v3, v155
	v_div_fixup_f32 v154, v2, v0, 1.0
	v_mul_u32_u24_e32 v0, 0x1a000, v183
	v_lshl_add_u64 v[2:3], v[152:153], 0, v[0:1]
	v_mul_f32_e32 v0, v27, v154
	v_mul_f32_e32 v0, v0, v138
	v_cvt_pk_bf16_f32 v0, v0, v1
	global_store_short v[2:3], v0, off
	v_mul_f32_e32 v0, v30, v154
	v_mul_f32_e32 v0, v0, v136
	v_cvt_pk_bf16_f32 v0, v0, v1
	global_store_short v[2:3], v0, off offset:64
	v_mul_f32_e32 v0, v44, v154
	v_mul_f32_e32 v0, v0, v137
	v_cvt_pk_bf16_f32 v0, v0, v1
	global_store_short v[2:3], v0, off offset:128
	v_mul_f32_e32 v0, v63, v154
	v_mul_f32_e32 v0, v0, v142
	v_cvt_pk_bf16_f32 v0, v0, v1
	global_store_short v[2:3], v0, off offset:192
	v_fmamk_f32 v0, v151, 0x3c000000, v219
	v_cmp_gt_f32_e32 vcc, s75, v0
	v_mul_f32_e32 v27, 0x4f800000, v0
	s_nop 0
	v_cndmask_b32_e32 v0, v0, v27, vcc
	v_sqrt_f32_e32 v27, v0
	s_nop 0
	v_add_u32_e32 v30, -1, v27
	v_fma_f32 v44, -v30, v27, v0
	v_cmp_ge_f32_e64 s[0:1], 0, v44
	v_add_u32_e32 v44, 1, v27
	s_nop 0
	v_cndmask_b32_e64 v30, v27, v30, s[0:1]
	v_fma_f32 v27, -v44, v27, v0
	v_cmp_lt_f32_e64 s[0:1], 0, v27
	s_nop 1
	v_cndmask_b32_e64 v27, v30, v44, s[0:1]
	v_mul_f32_e32 v30, 0x37800000, v27
	v_cndmask_b32_e32 v27, v27, v30, vcc
	v_cmp_class_f32_e32 vcc, v0, v220
	s_nop 1
	v_cndmask_b32_e32 v0, v27, v0, vcc
	v_div_scale_f32 v27, s[0:1], v0, v0, 1.0
	v_rcp_f32_e32 v30, v27
	s_movk_i32 s0, 0x6000
	v_fma_f32 v44, -v27, v30, 1.0
	v_fmac_f32_e32 v30, v44, v30
	v_div_scale_f32 v44, vcc, 1.0, v0, 1.0
	v_mul_f32_e32 v63, v44, v30
	v_fma_f32 v151, -v27, v63, v44
	v_fmac_f32_e32 v63, v151, v30
	v_fma_f32 v27, -v27, v63, v44
	v_div_fmas_f32 v27, v27, v30, v63
	v_div_fixup_f32 v0, v27, v0, 1.0
	v_mul_f32_e32 v27, v28, v0
	v_mul_f32_e32 v27, v27, v138
	v_add_co_u32_e32 v152, vcc, s0, v2
	v_cvt_pk_bf16_f32 v27, v27, v1
	s_nop 1
	v_addc_co_u32_e32 v153, vcc, 0, v3, vcc
	global_store_short v[152:153], v27, off offset:2048
	v_mul_f32_e32 v27, v41, v0
	v_mul_f32_e32 v27, v27, v136
	v_cvt_pk_bf16_f32 v27, v27, v1
	global_store_short v[152:153], v27, off offset:2112
	v_mul_f32_e32 v27, v47, v0
	v_mul_f32_e32 v0, v72, v0
	v_mul_f32_e32 v27, v27, v137
	v_mul_f32_e32 v0, v0, v142
	v_cvt_pk_bf16_f32 v27, v27, v1
	global_store_short v[152:153], v27, off offset:2176
	v_cvt_pk_bf16_f32 v0, v0, v1
	global_store_short v[152:153], v0, off offset:2240
	v_fmamk_f32 v0, v150, 0x3c000000, v219
	v_cmp_gt_f32_e32 vcc, s75, v0
	v_mul_f32_e32 v27, 0x4f800000, v0
	s_nop 0
	v_cndmask_b32_e32 v0, v0, v27, vcc
	v_sqrt_f32_e32 v27, v0
	s_nop 0
	v_add_u32_e32 v28, -1, v27
	v_fma_f32 v30, -v28, v27, v0
	v_cmp_ge_f32_e64 s[0:1], 0, v30
	v_add_u32_e32 v30, 1, v27
	s_nop 0
	v_cndmask_b32_e64 v28, v27, v28, s[0:1]
	v_fma_f32 v27, -v30, v27, v0
	v_cmp_lt_f32_e64 s[0:1], 0, v27
	s_nop 1
	v_cndmask_b32_e64 v27, v28, v30, s[0:1]
	v_mul_f32_e32 v28, 0x37800000, v27
	v_cndmask_b32_e32 v27, v27, v28, vcc
	v_cmp_class_f32_e32 vcc, v0, v220
	s_nop 1
	v_cndmask_b32_e32 v0, v27, v0, vcc
	v_div_scale_f32 v27, s[0:1], v0, v0, 1.0
	v_rcp_f32_e32 v28, v27
	s_mov_b32 s0, 0xd000
	v_fma_f32 v30, -v27, v28, 1.0
	v_fmac_f32_e32 v28, v30, v28
	v_div_scale_f32 v30, vcc, 1.0, v0, 1.0
	v_mul_f32_e32 v41, v30, v28
	v_fma_f32 v44, -v27, v41, v30
	v_fmac_f32_e32 v41, v44, v28
	v_fma_f32 v27, -v27, v41, v30
	v_div_fmas_f32 v27, v27, v28, v41
	v_div_fixup_f32 v0, v27, v0, 1.0
	v_mul_f32_e32 v27, v29, v0
	v_mul_f32_e32 v27, v27, v138
	v_add_co_u32_e32 v28, vcc, s0, v2
	v_cvt_pk_bf16_f32 v27, v27, v1
	s_nop 1
	v_addc_co_u32_e32 v29, vcc, 0, v3, vcc
	global_store_short v[28:29], v27, off
	v_mul_f32_e32 v27, v43, v0
; __device__ __forceinline__ unsigned cvt_pk_bf16(float lo, float hi) { unsigned r; asm volatile("v_cvt_pk_bf16_f32 %0, %1, %2" : "=v"(r) : "v"(lo), "v"(hi)); return r; }
; __device__ __forceinline__ int crow(int r, int hi) { return (r & 3) + 8 * (r >> 2) + 4 * hi; }
; __device__ __forceinline__ void unit(const bf16* __restrict__ Qb0, const bf16* __restrict__ Kh0, const bf16* __restrict__ Vh, bf16_t* Ob, int seq, char* lds, const int tid_in, const float lam, const float onem, const float* __restrict__ subw, const float* __restrict__ kmb  ) {
;     ...
;     for (int r = 0; r < 16; ++r) { const int orow = crow(r, hi); const float rs = 1.0f / sqrtf(ss[r] * (1.f / 128.f) + RMS_EPS);
; #pragma unroll
;       for (int d0 = 0; d0 < 4; ++d0) Ow[(long)orow * LDOB + d0 * 32 + r32] = (bf16_t)(cvt_pk_bf16(o[d0][r] * rs * sw[d0], 0.f) & 0xffffu); }
	v_mul_f32_e32 v27, v27, v136
	v_cvt_pk_bf16_f32 v27, v27, v1
	global_store_short v[28:29], v27, off offset:64
	v_mul_f32_e32 v27, v57, v0
	v_mul_f32_e32 v0, v76, v0
	v_mul_f32_e32 v27, v27, v137
	v_mul_f32_e32 v0, v0, v142
	v_cvt_pk_bf16_f32 v27, v27, v1
	global_store_short v[28:29], v27, off offset:128
	v_cvt_pk_bf16_f32 v0, v0, v1
	global_store_short v[28:29], v0, off offset:192
	v_fmamk_f32 v0, v149, 0x3c000000, v219
	v_cmp_gt_f32_e32 vcc, s75, v0
	v_mul_f32_e32 v27, 0x4f800000, v0
	s_nop 0
	v_cndmask_b32_e32 v0, v0, v27, vcc
	v_sqrt_f32_e32 v27, v0
	s_nop 0
	v_add_u32_e32 v28, -1, v27
	v_fma_f32 v29, -v28, v27, v0
	v_cmp_ge_f32_e64 s[0:1], 0, v29
	v_add_u32_e32 v29, 1, v27
	s_nop 0
	v_cndmask_b32_e64 v28, v27, v28, s[0:1]
	v_fma_f32 v27, -v29, v27, v0
	v_cmp_lt_f32_e64 s[0:1], 0, v27
	s_nop 1
	v_cndmask_b32_e64 v27, v28, v29, s[0:1]
	v_mul_f32_e32 v28, 0x37800000, v27
	v_cndmask_b32_e32 v27, v27, v28, vcc
	v_cmp_class_f32_e32 vcc, v0, v220
	s_nop 1
	v_cndmask_b32_e32 v0, v27, v0, vcc
	v_div_scale_f32 v27, s[0:1], v0, v0, 1.0
	v_rcp_f32_e32 v28, v27
	s_mov_b32 s0, 0x13000
	v_fma_f32 v29, -v27, v28, 1.0
	v_fmac_f32_e32 v28, v29, v28
	v_div_scale_f32 v29, vcc, 1.0, v0, 1.0
	v_mul_f32_e32 v30, v29, v28
	v_fma_f32 v41, -v27, v30, v29
	v_fmac_f32_e32 v30, v41, v28
	v_fma_f32 v27, -v27, v30, v29
	v_div_fmas_f32 v27, v27, v28, v30
	v_div_fixup_f32 v0, v27, v0, 1.0
	v_mul_f32_e32 v27, v31, v0
	v_mul_f32_e32 v27, v27, v138
	v_add_co_u32_e32 v28, vcc, s0, v2
	v_cvt_pk_bf16_f32 v27, v27, v1
	s_nop 1
	v_addc_co_u32_e32 v29, vcc, 0, v3, vcc
	global_store_short v[28:29], v27, off offset:2048
	v_mul_f32_e32 v27, v46, v0
	v_mul_f32_e32 v27, v27, v136
	v_cvt_pk_bf16_f32 v27, v27, v1
	global_store_short v[28:29], v27, off offset:2112
	v_mul_f32_e32 v27, v60, v0
	v_mul_f32_e32 v0, v101, v0
	v_mul_f32_e32 v27, v27, v137
	v_mul_f32_e32 v0, v0, v142
	v_cvt_pk_bf16_f32 v27, v27, v1
	global_store_short v[28:29], v27, off offset:2176
	v_cvt_pk_bf16_f32 v0, v0, v1
	global_store_short v[28:29], v0, off offset:2240
	v_fmamk_f32 v0, v148, 0x3c000000, v219
	v_cmp_gt_f32_e32 vcc, s75, v0
	v_mul_f32_e32 v27, 0x4f800000, v0
	s_nop 0
	v_cndmask_b32_e32 v0, v0, v27, vcc
	v_sqrt_f32_e32 v27, v0
	s_nop 0
	v_add_u32_e32 v28, -1, v27
	v_fma_f32 v29, -v28, v27, v0
	v_cmp_ge_f32_e64 s[0:1], 0, v29
	v_add_u32_e32 v29, 1, v27
	s_nop 0
	v_cndmask_b32_e64 v28, v27, v28, s[0:1]
	v_fma_f32 v27, -v29, v27, v0
	v_cmp_lt_f32_e64 s[0:1], 0, v27
	s_nop 1
	v_cndmask_b32_e64 v27, v28, v29, s[0:1]
	v_mul_f32_e32 v28, 0x37800000, v27
	v_cndmask_b32_e32 v27, v27, v28, vcc
	v_cmp_class_f32_e32 vcc, v0, v220
	s_nop 1
	v_cndmask_b32_e32 v0, v27, v0, vcc
	v_div_scale_f32 v27, s[0:1], v0, v0, 1.0
	v_rcp_f32_e32 v28, v27
	s_mov_b32 s0, 0x34000
	v_fma_f32 v29, -v27, v28, 1.0
	v_fmac_f32_e32 v28, v29, v28
	v_div_scale_f32 v29, vcc, 1.0, v0, 1.0
	v_mul_f32_e32 v30, v29, v28
	v_fma_f32 v31, -v27, v30, v29
	v_fmac_f32_e32 v30, v31, v28
	v_fma_f32 v27, -v27, v30, v29
	v_div_fmas_f32 v27, v27, v28, v30
	v_div_fixup_f32 v0, v27, v0, 1.0
	v_mul_f32_e32 v27, v42, v0
	v_mul_f32_e32 v27, v27, v138
	v_add_co_u32_e32 v28, vcc, s0, v2
	v_cvt_pk_bf16_f32 v27, v27, v1
	s_nop 1
	v_addc_co_u32_e32 v29, vcc, 0, v3, vcc
	global_store_short v[28:29], v27, off
	v_mul_f32_e32 v27, v56, v0
	v_mul_f32_e32 v27, v27, v136
	v_cvt_pk_bf16_f32 v27, v27, v1
	global_store_short v[28:29], v27, off offset:64
	v_mul_f32_e32 v27, v69, v0
	v_mul_f32_e32 v0, v105, v0
	v_mul_f32_e32 v27, v27, v137
	v_mul_f32_e32 v0, v0, v142
	v_cvt_pk_bf16_f32 v27, v27, v1
	global_store_short v[28:29], v27, off offset:128
	v_cvt_pk_bf16_f32 v0, v0, v1
	global_store_short v[28:29], v0, off offset:192
	v_fmamk_f32 v0, v147, 0x3c000000, v219
	v_cmp_gt_f32_e32 vcc, s75, v0
	v_mul_f32_e32 v27, 0x4f800000, v0
	s_nop 0
	v_cndmask_b32_e32 v0, v0, v27, vcc
	v_sqrt_f32_e32 v27, v0
	s_nop 0
	v_add_u32_e32 v28, -1, v27
	v_fma_f32 v29, -v28, v27, v0
	v_cmp_ge_f32_e64 s[0:1], 0, v29
	v_add_u32_e32 v29, 1, v27
	s_nop 0
	v_cndmask_b32_e64 v28, v27, v28, s[0:1]
	v_fma_f32 v27, -v29, v27, v0
	v_cmp_lt_f32_e64 s[0:1], 0, v27
	s_nop 1
	v_cndmask_b32_e64 v27, v28, v29, s[0:1]
	v_mul_f32_e32 v28, 0x37800000, v27
	v_cndmask_b32_e32 v27, v27, v28, vcc
	v_cmp_class_f32_e32 vcc, v0, v220
	s_nop 1
	v_cndmask_b32_e32 v0, v27, v0, vcc
	v_div_scale_f32 v27, s[0:1], v0, v0, 1.0
	v_rcp_f32_e32 v28, v27
	s_mov_b32 s0, 0x3a000
	v_fma_f32 v29, -v27, v28, 1.0
	v_fmac_f32_e32 v28, v29, v28
	v_div_scale_f32 v29, vcc, 1.0, v0, 1.0
	v_mul_f32_e32 v30, v29, v28
	v_fma_f32 v31, -v27, v30, v29
	v_fmac_f32_e32 v30, v31, v28
	v_fma_f32 v27, -v27, v30, v29
	v_div_fmas_f32 v27, v27, v28, v30
	v_div_fixup_f32 v0, v27, v0, 1.0
	v_mul_f32_e32 v27, v45, v0
	v_mul_f32_e32 v27, v27, v138
	v_add_co_u32_e32 v28, vcc, s0, v2
	v_cvt_pk_bf16_f32 v27, v27, v1
	s_nop 1
	v_addc_co_u32_e32 v29, vcc, 0, v3, vcc
	global_store_short v[28:29], v27, off offset:2048
	v_mul_f32_e32 v27, v59, v0
	v_mul_f32_e32 v27, v27, v136
	v_cvt_pk_bf16_f32 v27, v27, v1
	global_store_short v[28:29], v27, off offset:2112
	v_mul_f32_e32 v27, v73, v0
	v_mul_f32_e32 v0, v109, v0
	v_mul_f32_e32 v27, v27, v137
	v_mul_f32_e32 v0, v0, v142
	v_cvt_pk_bf16_f32 v27, v27, v1
	global_store_short v[28:29], v27, off offset:2176
	v_cvt_pk_bf16_f32 v0, v0, v1
	global_store_short v[28:29], v0, off offset:2240
	v_fmamk_f32 v0, v146, 0x3c000000, v219
	v_cmp_gt_f32_e32 vcc, s75, v0
	v_mul_f32_e32 v27, 0x4f800000, v0
	s_nop 0
	v_cndmask_b32_e32 v0, v0, v27, vcc
	v_sqrt_f32_e32 v27, v0
	s_nop 0
	v_add_u32_e32 v28, -1, v27
	v_fma_f32 v29, -v28, v27, v0
	v_cmp_ge_f32_e64 s[0:1], 0, v29
	v_add_u32_e32 v29, 1, v27
	s_nop 0
	v_cndmask_b32_e64 v28, v27, v28, s[0:1]
; __device__ __forceinline__ unsigned cvt_pk_bf16(float lo, float hi) { unsigned r; asm volatile("v_cvt_pk_bf16_f32 %0, %1, %2" : "=v"(r) : "v"(lo), "v"(hi)); return r; }
; __device__ __forceinline__ int crow(int r, int hi) { return (r & 3) + 8 * (r >> 2) + 4 * hi; }
; __device__ __forceinline__ void unit(const bf16* __restrict__ Qb0, const bf16* __restrict__ Kh0, const bf16* __restrict__ Vh, bf16_t* Ob, int seq, char* lds, const int tid_in, const float lam, const float onem, const float* __restrict__ subw, const float* __restrict__ kmb  ) {
;     ...
;     for (int r = 0; r < 16; ++r) { const int orow = crow(r, hi); const float rs = 1.0f / sqrtf(ss[r] * (1.f / 128.f) + RMS_EPS);
; #pragma unroll
;       for (int d0 = 0; d0 < 4; ++d0) Ow[(long)orow * LDOB + d0 * 32 + r32] = (bf16_t)(cvt_pk_bf16(o[d0][r] * rs * sw[d0], 0.f) & 0xffffu); }
	v_fma_f32 v27, -v29, v27, v0
	v_cmp_lt_f32_e64 s[0:1], 0, v27
	s_nop 1
	v_cndmask_b32_e64 v27, v28, v29, s[0:1]
	v_mul_f32_e32 v28, 0x37800000, v27
	v_cndmask_b32_e32 v27, v27, v28, vcc
	v_cmp_class_f32_e32 vcc, v0, v220
	s_nop 1
	v_cndmask_b32_e32 v0, v27, v0, vcc
	v_div_scale_f32 v27, s[0:1], v0, v0, 1.0
	v_rcp_f32_e32 v28, v27
	s_mov_b32 s0, 0x41000
	v_fma_f32 v29, -v27, v28, 1.0
	v_fmac_f32_e32 v28, v29, v28
	v_div_scale_f32 v29, vcc, 1.0, v0, 1.0
	v_mul_f32_e32 v30, v29, v28
	v_fma_f32 v31, -v27, v30, v29
	v_fmac_f32_e32 v30, v31, v28
	v_fma_f32 v27, -v27, v30, v29
	v_div_fmas_f32 v27, v27, v28, v30
	v_div_fixup_f32 v0, v27, v0, 1.0
	v_mul_f32_e32 v27, v55, v0
	v_mul_f32_e32 v27, v27, v138
	v_add_co_u32_e32 v28, vcc, s0, v2
	v_cvt_pk_bf16_f32 v27, v27, v1
	s_nop 1
	v_addc_co_u32_e32 v29, vcc, 0, v3, vcc
	global_store_short v[28:29], v27, off
	v_mul_f32_e32 v27, v62, v0
	v_mul_f32_e32 v27, v27, v136
	v_cvt_pk_bf16_f32 v27, v27, v1
	global_store_short v[28:29], v27, off offset:64
	v_mul_f32_e32 v27, v77, v0
	v_mul_f32_e32 v0, v113, v0
	v_mul_f32_e32 v27, v27, v137
	v_mul_f32_e32 v0, v0, v142
	v_cvt_pk_bf16_f32 v27, v27, v1
	global_store_short v[28:29], v27, off offset:128
	v_cvt_pk_bf16_f32 v0, v0, v1
	global_store_short v[28:29], v0, off offset:192
	v_fmamk_f32 v0, v145, 0x3c000000, v219
	v_cmp_gt_f32_e32 vcc, s75, v0
	v_mul_f32_e32 v27, 0x4f800000, v0
	s_nop 0
	v_cndmask_b32_e32 v0, v0, v27, vcc
	v_sqrt_f32_e32 v27, v0
	s_nop 0
	v_add_u32_e32 v28, -1, v27
	v_fma_f32 v29, -v28, v27, v0
	v_cmp_ge_f32_e64 s[0:1], 0, v29
	v_add_u32_e32 v29, 1, v27
	s_nop 0
	v_cndmask_b32_e64 v28, v27, v28, s[0:1]
	v_fma_f32 v27, -v29, v27, v0
	v_cmp_lt_f32_e64 s[0:1], 0, v27
	s_nop 1
	v_cndmask_b32_e64 v27, v28, v29, s[0:1]
	v_mul_f32_e32 v28, 0x37800000, v27
	v_cndmask_b32_e32 v27, v27, v28, vcc
	v_cmp_class_f32_e32 vcc, v0, v220
	s_nop 1
	v_cndmask_b32_e32 v0, v27, v0, vcc
	v_div_scale_f32 v27, s[0:1], v0, v0, 1.0
	v_rcp_f32_e32 v28, v27
	s_mov_b32 s0, 0x47000
	v_fma_f32 v29, -v27, v28, 1.0
	v_fmac_f32_e32 v28, v29, v28
	v_div_scale_f32 v29, vcc, 1.0, v0, 1.0
	v_mul_f32_e32 v30, v29, v28
	v_fma_f32 v31, -v27, v30, v29
	v_fmac_f32_e32 v30, v31, v28
	v_fma_f32 v27, -v27, v30, v29
	v_div_fmas_f32 v27, v27, v28, v30
	v_div_fixup_f32 v0, v27, v0, 1.0
	v_mul_f32_e32 v27, v58, v0
	v_mul_f32_e32 v27, v27, v138
	v_add_co_u32_e32 v28, vcc, s0, v2
	v_cvt_pk_bf16_f32 v27, v27, v1
	s_nop 1
	v_addc_co_u32_e32 v29, vcc, 0, v3, vcc
	global_store_short v[28:29], v27, off offset:2048
	v_mul_f32_e32 v27, v71, v0
	v_mul_f32_e32 v27, v27, v136
	v_cvt_pk_bf16_f32 v27, v27, v1
	global_store_short v[28:29], v27, off offset:2112
	v_mul_f32_e32 v27, v102, v0
	v_mul_f32_e32 v0, v117, v0
	v_mul_f32_e32 v27, v27, v137
	v_mul_f32_e32 v0, v0, v142
	v_cvt_pk_bf16_f32 v27, v27, v1
	global_store_short v[28:29], v27, off offset:2176
	v_cvt_pk_bf16_f32 v0, v0, v1
	global_store_short v[28:29], v0, off offset:2240
	v_fmamk_f32 v0, v144, 0x3c000000, v219
	v_cmp_gt_f32_e32 vcc, s75, v0
	v_mul_f32_e32 v27, 0x4f800000, v0
	s_nop 0
	v_cndmask_b32_e32 v0, v0, v27, vcc
	v_sqrt_f32_e32 v27, v0
	s_nop 0
	v_add_u32_e32 v28, -1, v27
	v_fma_f32 v29, -v28, v27, v0
	v_cmp_ge_f32_e64 s[0:1], 0, v29
	v_add_u32_e32 v29, 1, v27
	s_nop 0
	v_cndmask_b32_e64 v28, v27, v28, s[0:1]
	v_fma_f32 v27, -v29, v27, v0
	v_cmp_lt_f32_e64 s[0:1], 0, v27
	s_nop 1
	v_cndmask_b32_e64 v27, v28, v29, s[0:1]
	v_mul_f32_e32 v28, 0x37800000, v27
	v_cndmask_b32_e32 v27, v27, v28, vcc
	v_cmp_class_f32_e32 vcc, v0, v220
	s_nop 1
	v_cndmask_b32_e32 v0, v27, v0, vcc
	v_div_scale_f32 v27, s[0:1], v0, v0, 1.0
	v_rcp_f32_e32 v28, v27
	s_mov_b32 s0, 0x68000
	v_fma_f32 v29, -v27, v28, 1.0
	v_fmac_f32_e32 v28, v29, v28
	v_div_scale_f32 v29, vcc, 1.0, v0, 1.0
	v_mul_f32_e32 v30, v29, v28
	v_fma_f32 v31, -v27, v30, v29
	v_fmac_f32_e32 v30, v31, v28
	v_fma_f32 v27, -v27, v30, v29
	v_div_fmas_f32 v27, v27, v28, v30
	v_div_fixup_f32 v0, v27, v0, 1.0
	v_mul_f32_e32 v27, v61, v0
	v_mul_f32_e32 v27, v27, v138
	v_add_co_u32_e32 v28, vcc, s0, v2
	v_cvt_pk_bf16_f32 v27, v27, v1
	s_nop 1
	v_addc_co_u32_e32 v29, vcc, 0, v3, vcc
	global_store_short v[28:29], v27, off
	v_mul_f32_e32 v27, v75, v0
	v_mul_f32_e32 v27, v27, v136
	v_cvt_pk_bf16_f32 v27, v27, v1
	global_store_short v[28:29], v27, off offset:64
	v_mul_f32_e32 v27, v106, v0
	v_mul_f32_e32 v0, v120, v0
	v_mul_f32_e32 v27, v27, v137
	v_mul_f32_e32 v0, v0, v142
	v_cvt_pk_bf16_f32 v27, v27, v1
	global_store_short v[28:29], v27, off offset:128
	v_cvt_pk_bf16_f32 v0, v0, v1
	global_store_short v[28:29], v0, off offset:192
	v_fmamk_f32 v0, v143, 0x3c000000, v219
	v_cmp_gt_f32_e32 vcc, s75, v0
	v_mul_f32_e32 v27, 0x4f800000, v0
	s_nop 0
	v_cndmask_b32_e32 v0, v0, v27, vcc
	v_sqrt_f32_e32 v27, v0
	s_nop 0
	v_add_u32_e32 v28, -1, v27
	v_fma_f32 v29, -v28, v27, v0
	v_cmp_ge_f32_e64 s[0:1], 0, v29
	v_add_u32_e32 v29, 1, v27
	s_nop 0
	v_cndmask_b32_e64 v28, v27, v28, s[0:1]
	v_fma_f32 v27, -v29, v27, v0
	v_cmp_lt_f32_e64 s[0:1], 0, v27
	s_nop 1
	v_cndmask_b32_e64 v27, v28, v29, s[0:1]
	v_mul_f32_e32 v28, 0x37800000, v27
	v_cndmask_b32_e32 v27, v27, v28, vcc
	v_cmp_class_f32_e32 vcc, v0, v220
	s_nop 1
	v_cndmask_b32_e32 v0, v27, v0, vcc
	v_div_scale_f32 v27, s[0:1], v0, v0, 1.0
	v_rcp_f32_e32 v28, v27
	s_mov_b32 s0, 0x6e000
	v_fma_f32 v29, -v27, v28, 1.0
	v_fmac_f32_e32 v28, v29, v28
	v_div_scale_f32 v29, vcc, 1.0, v0, 1.0
	v_mul_f32_e32 v30, v29, v28
	v_fma_f32 v31, -v27, v30, v29
	v_fmac_f32_e32 v30, v31, v28
	v_fma_f32 v27, -v27, v30, v29
	v_div_fmas_f32 v27, v27, v28, v30
	v_div_fixup_f32 v0, v27, v0, 1.0
	v_mul_f32_e32 v27, v70, v0
	v_mul_f32_e32 v27, v27, v138
	v_add_co_u32_e32 v28, vcc, s0, v2
; __device__ __forceinline__ unsigned cvt_pk_bf16(float lo, float hi) { unsigned r; asm volatile("v_cvt_pk_bf16_f32 %0, %1, %2" : "=v"(r) : "v"(lo), "v"(hi)); return r; }
; __device__ __forceinline__ int crow(int r, int hi) { return (r & 3) + 8 * (r >> 2) + 4 * hi; }
; __device__ __forceinline__ void unit(const bf16* __restrict__ Qb0, const bf16* __restrict__ Kh0, const bf16* __restrict__ Vh, bf16_t* Ob, int seq, char* lds, const int tid_in, const float lam, const float onem, const float* __restrict__ subw, const float* __restrict__ kmb  ) {
;     ...
;     for (int r = 0; r < 16; ++r) { const int orow = crow(r, hi); const float rs = 1.0f / sqrtf(ss[r] * (1.f / 128.f) + RMS_EPS);
; #pragma unroll
;       for (int d0 = 0; d0 < 4; ++d0) Ow[(long)orow * LDOB + d0 * 32 + r32] = (bf16_t)(cvt_pk_bf16(o[d0][r] * rs * sw[d0], 0.f) & 0xffffu); }
	v_cvt_pk_bf16_f32 v27, v27, v1
	s_nop 1
	v_addc_co_u32_e32 v29, vcc, 0, v3, vcc
	global_store_short v[28:29], v27, off offset:2048
	v_mul_f32_e32 v27, v79, v0
	v_mul_f32_e32 v27, v27, v136
	v_cvt_pk_bf16_f32 v27, v27, v1
	global_store_short v[28:29], v27, off offset:2112
	v_mul_f32_e32 v27, v110, v0
	v_mul_f32_e32 v0, v123, v0
	v_mul_f32_e32 v27, v27, v137
	v_mul_f32_e32 v0, v0, v142
	v_cvt_pk_bf16_f32 v27, v27, v1
	global_store_short v[28:29], v27, off offset:2176
	v_cvt_pk_bf16_f32 v0, v0, v1
	global_store_short v[28:29], v0, off offset:2240
	v_fmamk_f32 v0, v141, 0x3c000000, v219
	v_cmp_gt_f32_e32 vcc, s75, v0
	v_mul_f32_e32 v27, 0x4f800000, v0
	s_nop 0
	v_cndmask_b32_e32 v0, v0, v27, vcc
	v_sqrt_f32_e32 v27, v0
	s_nop 0
	v_add_u32_e32 v28, -1, v27
	v_fma_f32 v29, -v28, v27, v0
	v_cmp_ge_f32_e64 s[0:1], 0, v29
	v_add_u32_e32 v29, 1, v27
	s_nop 0
	v_cndmask_b32_e64 v28, v27, v28, s[0:1]
	v_fma_f32 v27, -v29, v27, v0
	v_cmp_lt_f32_e64 s[0:1], 0, v27
	s_nop 1
	v_cndmask_b32_e64 v27, v28, v29, s[0:1]
	v_mul_f32_e32 v28, 0x37800000, v27
	v_cndmask_b32_e32 v27, v27, v28, vcc
	v_cmp_class_f32_e32 vcc, v0, v220
	s_nop 1
	v_cndmask_b32_e32 v0, v27, v0, vcc
	v_div_scale_f32 v27, s[0:1], v0, v0, 1.0
	v_rcp_f32_e32 v28, v27
	s_mov_b32 s0, 0x75000
	v_fma_f32 v29, -v27, v28, 1.0
	v_fmac_f32_e32 v28, v29, v28
	v_div_scale_f32 v29, vcc, 1.0, v0, 1.0
	v_mul_f32_e32 v30, v29, v28
	v_fma_f32 v31, -v27, v30, v29
	v_fmac_f32_e32 v30, v31, v28
	v_fma_f32 v27, -v27, v30, v29
	v_div_fmas_f32 v27, v27, v28, v30
	v_div_fixup_f32 v0, v27, v0, 1.0
	v_mul_f32_e32 v27, v74, v0
	v_mul_f32_e32 v27, v138, v27
	v_add_co_u32_e32 v28, vcc, s0, v2
	v_cvt_pk_bf16_f32 v27, v27, v1
	s_nop 1
	v_addc_co_u32_e32 v29, vcc, 0, v3, vcc
	global_store_short v[28:29], v27, off
	v_mul_f32_e32 v27, v104, v0
	v_mul_f32_e32 v27, v27, v136
	v_cvt_pk_bf16_f32 v27, v27, v1
	global_store_short v[28:29], v27, off offset:64
	v_mul_f32_e32 v27, v114, v0
	v_mul_f32_e32 v0, v125, v0
	v_mul_f32_e32 v27, v27, v137
	v_mul_f32_e32 v0, v0, v142
	v_cvt_pk_bf16_f32 v27, v27, v1
	global_store_short v[28:29], v27, off offset:128
	v_cvt_pk_bf16_f32 v0, v0, v1
	global_store_short v[28:29], v0, off offset:192
	v_fmamk_f32 v0, v140, 0x3c000000, v219
	v_cmp_gt_f32_e32 vcc, s75, v0
	v_mul_f32_e32 v27, 0x4f800000, v0
	s_nop 0
	v_cndmask_b32_e32 v0, v0, v27, vcc
	v_sqrt_f32_e32 v27, v0
	s_nop 0
	v_add_u32_e32 v28, -1, v27
	v_fma_f32 v29, -v28, v27, v0
	v_cmp_ge_f32_e64 s[0:1], 0, v29
	v_add_u32_e32 v29, 1, v27
	s_nop 0
	v_cndmask_b32_e64 v28, v27, v28, s[0:1]
	v_fma_f32 v27, -v29, v27, v0
	v_cmp_lt_f32_e64 s[0:1], 0, v27
	s_nop 1
	v_cndmask_b32_e64 v27, v28, v29, s[0:1]
	v_mul_f32_e32 v28, 0x37800000, v27
	v_cndmask_b32_e32 v27, v27, v28, vcc
	v_cmp_class_f32_e32 vcc, v0, v220
	s_nop 1
	v_cndmask_b32_e32 v0, v27, v0, vcc
	v_div_scale_f32 v27, s[0:1], v0, v0, 1.0
	v_rcp_f32_e32 v28, v27
	s_mov_b32 s0, 0x7b000
	v_fma_f32 v29, -v27, v28, 1.0
	v_fmac_f32_e32 v28, v29, v28
	v_div_scale_f32 v29, vcc, 1.0, v0, 1.0
	v_mul_f32_e32 v30, v29, v28
	v_fma_f32 v31, -v27, v30, v29
	v_fmac_f32_e32 v30, v31, v28
	v_fma_f32 v27, -v27, v30, v29
	v_div_fmas_f32 v27, v27, v28, v30
	v_div_fixup_f32 v0, v27, v0, 1.0
	v_mul_f32_e32 v27, v78, v0
	v_mul_f32_e32 v27, v138, v27
	v_add_co_u32_e32 v28, vcc, s0, v2
	v_cvt_pk_bf16_f32 v27, v27, v1
	s_nop 1
	v_addc_co_u32_e32 v29, vcc, 0, v3, vcc
	global_store_short v[28:29], v27, off offset:2048
	v_mul_f32_e32 v27, v108, v0
	v_mul_f32_e32 v27, v136, v27
	v_cvt_pk_bf16_f32 v27, v27, v1
	global_store_short v[28:29], v27, off offset:2112
	v_mul_f32_e32 v27, v118, v0
	v_mul_f32_e32 v0, v127, v0
	v_mul_f32_e32 v27, v27, v137
	v_mul_f32_e32 v0, v0, v142
	v_cvt_pk_bf16_f32 v27, v27, v1
	global_store_short v[28:29], v27, off offset:2176
	v_cvt_pk_bf16_f32 v0, v0, v1
	global_store_short v[28:29], v0, off offset:2240
	v_fmamk_f32 v0, v139, 0x3c000000, v219
	v_cmp_gt_f32_e32 vcc, s75, v0
	v_mul_f32_e32 v27, 0x4f800000, v0
	s_nop 0
	v_cndmask_b32_e32 v0, v0, v27, vcc
	v_sqrt_f32_e32 v27, v0
	s_nop 0
	v_add_u32_e32 v28, -1, v27
	v_fma_f32 v29, -v28, v27, v0
	v_cmp_ge_f32_e64 s[0:1], 0, v29
	v_add_u32_e32 v29, 1, v27
	s_nop 0
	v_cndmask_b32_e64 v28, v27, v28, s[0:1]
	v_fma_f32 v27, -v29, v27, v0
	v_cmp_lt_f32_e64 s[0:1], 0, v27
	s_nop 1
	v_cndmask_b32_e64 v27, v28, v29, s[0:1]
	v_mul_f32_e32 v28, 0x37800000, v27
	v_cndmask_b32_e32 v27, v27, v28, vcc
	v_cmp_class_f32_e32 vcc, v0, v220
	s_nop 1
	v_cndmask_b32_e32 v0, v27, v0, vcc
	v_div_scale_f32 v27, s[0:1], v0, v0, 1.0
	v_rcp_f32_e32 v28, v27
	s_mov_b32 s0, 0x9c000
	v_fma_f32 v29, -v27, v28, 1.0
	v_fmac_f32_e32 v28, v29, v28
	v_div_scale_f32 v29, vcc, 1.0, v0, 1.0
	v_mul_f32_e32 v30, v29, v28
	v_fma_f32 v31, -v27, v30, v29
	v_fmac_f32_e32 v30, v31, v28
	v_fma_f32 v27, -v27, v30, v29
	v_div_fmas_f32 v27, v27, v28, v30
	v_div_fixup_f32 v0, v27, v0, 1.0
	v_mul_f32_e32 v27, v103, v0
	v_mul_f32_e32 v27, v138, v27
	v_add_co_u32_e32 v28, vcc, s0, v2
	v_cvt_pk_bf16_f32 v27, v27, v1
	s_nop 1
	v_addc_co_u32_e32 v29, vcc, 0, v3, vcc
	global_store_short v[28:29], v27, off
	v_mul_f32_e32 v27, v112, v0
	v_mul_f32_e32 v27, v136, v27
	v_cvt_pk_bf16_f32 v27, v27, v1
	global_store_short v[28:29], v27, off offset:64
	v_mul_f32_e32 v27, v121, v0
; __device__ __forceinline__ unsigned cvt_pk_bf16(float lo, float hi) { unsigned r; asm volatile("v_cvt_pk_bf16_f32 %0, %1, %2" : "=v"(r) : "v"(lo), "v"(hi)); return r; }
; __device__ __forceinline__ int crow(int r, int hi) { return (r & 3) + 8 * (r >> 2) + 4 * hi; }
; __device__ __forceinline__ void unit(const bf16* __restrict__ Qb0, const bf16* __restrict__ Kh0, const bf16* __restrict__ Vh, bf16_t* Ob, int seq, char* lds, const int tid_in, const float lam, const float onem, const float* __restrict__ subw, const float* __restrict__ kmb  ) {
;     ...
;     for (int r = 0; r < 16; ++r) { const int orow = crow(r, hi); const float rs = 1.0f / sqrtf(ss[r] * (1.f / 128.f) + RMS_EPS);
; #pragma unroll
;       for (int d0 = 0; d0 < 4; ++d0) Ow[(long)orow * LDOB + d0 * 32 + r32] = (bf16_t)(cvt_pk_bf16(o[d0][r] * rs * sw[d0], 0.f) & 0xffffu); }
	v_mul_f32_e32 v0, v129, v0
	v_mul_f32_e32 v27, v137, v27
	v_mul_f32_e32 v0, v0, v142
	v_cvt_pk_bf16_f32 v27, v27, v1
	global_store_short v[28:29], v27, off offset:128
	v_cvt_pk_bf16_f32 v0, v0, v1
	global_store_short v[28:29], v0, off offset:192
	v_fmamk_f32 v0, v135, 0x3c000000, v219
	v_cmp_gt_f32_e32 vcc, s75, v0
	v_mul_f32_e32 v27, 0x4f800000, v0
	s_nop 0
	v_cndmask_b32_e32 v0, v0, v27, vcc
	v_sqrt_f32_e32 v27, v0
	s_nop 0
	v_add_u32_e32 v28, -1, v27
	v_fma_f32 v29, -v28, v27, v0
	v_cmp_ge_f32_e64 s[0:1], 0, v29
	v_add_u32_e32 v29, 1, v27
	s_nop 0
	v_cndmask_b32_e64 v28, v27, v28, s[0:1]
	v_fma_f32 v27, -v29, v27, v0
	v_cmp_lt_f32_e64 s[0:1], 0, v27
	s_nop 1
	v_cndmask_b32_e64 v27, v28, v29, s[0:1]
	v_mul_f32_e32 v28, 0x37800000, v27
	v_cndmask_b32_e32 v27, v27, v28, vcc
	v_cmp_class_f32_e32 vcc, v0, v220
	s_nop 1
	v_cndmask_b32_e32 v0, v27, v0, vcc
	v_div_scale_f32 v27, s[0:1], v0, v0, 1.0
	v_rcp_f32_e32 v28, v27
	s_mov_b32 s0, 0xa2000
	v_fma_f32 v29, -v27, v28, 1.0
	v_fmac_f32_e32 v28, v29, v28
	v_div_scale_f32 v29, vcc, 1.0, v0, 1.0
	v_mul_f32_e32 v30, v29, v28
	v_fma_f32 v31, -v27, v30, v29
	v_fmac_f32_e32 v30, v31, v28
	v_fma_f32 v27, -v27, v30, v29
	v_div_fmas_f32 v27, v27, v28, v30
	v_div_fixup_f32 v0, v27, v0, 1.0
	v_mul_f32_e32 v27, v107, v0
	v_mul_f32_e32 v27, v138, v27
	v_add_co_u32_e32 v28, vcc, s0, v2
	v_cvt_pk_bf16_f32 v27, v27, v1
	s_nop 1
	v_addc_co_u32_e32 v29, vcc, 0, v3, vcc
	global_store_short v[28:29], v27, off offset:2048
	v_mul_f32_e32 v27, v116, v0
	v_mul_f32_e32 v27, v136, v27
	v_cvt_pk_bf16_f32 v27, v27, v1
	global_store_short v[28:29], v27, off offset:2112
	v_mul_f32_e32 v27, v124, v0
	v_mul_f32_e32 v0, v130, v0
	v_mul_f32_e32 v27, v137, v27
	v_mul_f32_e32 v0, v142, v0
	v_cvt_pk_bf16_f32 v27, v27, v1
	global_store_short v[28:29], v27, off offset:2176
	v_cvt_pk_bf16_f32 v0, v0, v1
	global_store_short v[28:29], v0, off offset:2240
	v_fmamk_f32 v0, v134, 0x3c000000, v219
	v_cmp_gt_f32_e32 vcc, s75, v0
	v_mul_f32_e32 v27, 0x4f800000, v0
	s_nop 0
	v_cndmask_b32_e32 v0, v0, v27, vcc
	v_sqrt_f32_e32 v27, v0
	s_nop 0
	v_add_u32_e32 v28, -1, v27
	v_fma_f32 v29, -v28, v27, v0
	v_cmp_ge_f32_e64 s[0:1], 0, v29
	v_add_u32_e32 v29, 1, v27
	s_nop 0
	v_cndmask_b32_e64 v28, v27, v28, s[0:1]
	v_fma_f32 v27, -v29, v27, v0
	v_cmp_lt_f32_e64 s[0:1], 0, v27
	s_nop 1
	v_cndmask_b32_e64 v27, v28, v29, s[0:1]
	v_mul_f32_e32 v28, 0x37800000, v27
	v_cndmask_b32_e32 v27, v27, v28, vcc
	v_cmp_class_f32_e32 vcc, v0, v220
	s_nop 1
	v_cndmask_b32_e32 v0, v27, v0, vcc
	v_div_scale_f32 v27, s[0:1], v0, v0, 1.0
	v_rcp_f32_e32 v28, v27
	s_mov_b32 s0, 0xa9000
	v_fma_f32 v29, -v27, v28, 1.0
	v_fmac_f32_e32 v28, v29, v28
	v_div_scale_f32 v29, vcc, 1.0, v0, 1.0
	v_mul_f32_e32 v30, v29, v28
	v_fma_f32 v31, -v27, v30, v29
	v_fmac_f32_e32 v30, v31, v28
	v_fma_f32 v27, -v27, v30, v29
	v_div_fmas_f32 v27, v27, v28, v30
	v_div_fixup_f32 v0, v27, v0, 1.0
	v_mul_f32_e32 v27, v111, v0
	v_mul_f32_e32 v27, v138, v27
	v_add_co_u32_e32 v28, vcc, s0, v2
	v_cvt_pk_bf16_f32 v27, v27, v1
	s_nop 1
	v_addc_co_u32_e32 v29, vcc, 0, v3, vcc
	global_store_short v[28:29], v27, off
	v_mul_f32_e32 v27, v119, v0
	v_mul_f32_e32 v27, v136, v27
	v_cvt_pk_bf16_f32 v27, v27, v1
	global_store_short v[28:29], v27, off offset:64
	v_mul_f32_e32 v27, v126, v0
	v_mul_f32_e32 v0, v131, v0
	v_mul_f32_e32 v27, v137, v27
	v_mul_f32_e32 v0, v142, v0
	v_cvt_pk_bf16_f32 v27, v27, v1
	global_store_short v[28:29], v27, off offset:128
	v_cvt_pk_bf16_f32 v0, v0, v1
	global_store_short v[28:29], v0, off offset:192
	v_fmamk_f32 v0, v133, 0x3c000000, v219
	v_cmp_gt_f32_e32 vcc, s75, v0
	v_mul_f32_e32 v27, 0x4f800000, v0
	s_nop 0
	v_cndmask_b32_e32 v0, v0, v27, vcc
	v_sqrt_f32_e32 v27, v0
	s_nop 0
	v_add_u32_e32 v28, -1, v27
	v_fma_f32 v29, -v28, v27, v0
	v_cmp_ge_f32_e64 s[0:1], 0, v29
	v_add_u32_e32 v29, 1, v27
	s_nop 0
	v_cndmask_b32_e64 v28, v27, v28, s[0:1]
	v_fma_f32 v27, -v29, v27, v0
	v_cmp_lt_f32_e64 s[0:1], 0, v27
	s_nop 1
	v_cndmask_b32_e64 v27, v28, v29, s[0:1]
	v_mul_f32_e32 v28, 0x37800000, v27
	v_cndmask_b32_e32 v27, v27, v28, vcc
	v_cmp_class_f32_e32 vcc, v0, v220
	s_nop 1
	v_cndmask_b32_e32 v0, v27, v0, vcc
	v_div_scale_f32 v27, s[0:1], v0, v0, 1.0
	v_rcp_f32_e32 v28, v27
	s_mov_b32 s0, 0xaf000
	v_fma_f32 v29, -v27, v28, 1.0
	v_fmac_f32_e32 v28, v29, v28
	v_div_scale_f32 v29, vcc, 1.0, v0, 1.0
	v_mul_f32_e32 v30, v29, v28
	v_fma_f32 v31, -v27, v30, v29
	v_fmac_f32_e32 v30, v31, v28
	v_fma_f32 v27, -v27, v30, v29
	v_div_fmas_f32 v27, v27, v28, v30
	v_div_fixup_f32 v0, v27, v0, 1.0
	v_mul_f32_e32 v27, v115, v0
	v_mul_f32_e32 v27, v138, v27
	v_add_co_u32_e32 v2, vcc, s0, v2
	v_cvt_pk_bf16_f32 v27, v27, v1
	s_mov_b64 s[0:1], 0
	s_nop 0
	v_addc_co_u32_e32 v3, vcc, 0, v3, vcc
	global_store_short v[2:3], v27, off offset:2048
	v_mul_f32_e32 v27, v122, v0
	v_mul_f32_e32 v27, v136, v27
	v_cvt_pk_bf16_f32 v27, v27, v1
	global_store_short v[2:3], v27, off offset:2112
	v_mul_f32_e32 v27, v128, v0
	v_mul_f32_e32 v0, v132, v0
	v_mul_f32_e32 v27, v137, v27
	v_mul_f32_e32 v0, v142, v0
	v_cvt_pk_bf16_f32 v27, v27, v1
	global_store_short v[2:3], v27, off offset:2176
	v_cvt_pk_bf16_f32 v0, v0, v1
	global_store_short v[2:3], v0, off offset:2240
